# pool items: weight loads issued before waiting on u-tile loads; buffer_inv moved ahead of the spin / off the release path in local and global barriers; in-proj to phase-B global barrier replaced by pe
# speedup vs baseline: 1.2068x; 1.0681x over previous
.LBB0_69:
	s_or_b64 exec, exec, s[10:11]
	v_cvt_f32_u32_e32 v4, v2
	s_waitcnt vmcnt(0)
	v_readfirstlane_b32 s8, v3
	v_sub_u32_e32 v3, 0, v2
	v_rcp_iflag_f32_e32 v4, v4
	v_add_u32_e32 v5, s8, v1
	v_mul_f32_e32 v4, 0x4f7ffffe, v4
	v_cvt_u32_f32_e32 v4, v4
	v_mul_lo_u32 v1, v3, v4
	v_mul_hi_u32 v1, v4, v1
	v_add_u32_e32 v1, v4, v1
	v_mul_hi_u32 v1, v5, v1
	v_mul_lo_u32 v3, v1, v2
	v_sub_u32_e32 v3, v5, v3
	v_add_u32_e32 v4, 1, v1
	v_cmp_ge_u32_e32 vcc, v3, v2
	s_nop 1
	v_cndmask_b32_e32 v1, v1, v4, vcc
	v_sub_u32_e32 v4, v3, v2
	v_cndmask_b32_e32 v3, v3, v4, vcc
	v_add_u32_e32 v4, 1, v1
	v_cmp_ge_u32_e32 vcc, v3, v2
	v_add_u32_e32 v3, 1, v5
	s_nop 0
	v_cndmask_b32_e32 v1, v1, v4, vcc
	v_mul_lo_u32 v4, v2, v1
	v_add_u32_e32 v2, v4, v2
	v_cmp_ne_u32_e32 vcc, v3, v2
	s_and_saveexec_b64 s[8:9], vcc
	s_xor_b64 s[8:9], exec, s[8:9]
	s_cbranch_execz .LBB0_83
	s_waitcnt lgkmcnt(0)
	buffer_inv sc1
	v_mov_b32_e32 v0, 0x2000
	global_load_dword v0, v0, s[6:7] offset:1024 sc1
	s_add_u32 s12, s6, 0x2400
	s_addc_u32 s13, s7, 0
	s_waitcnt vmcnt(0)
	v_cmp_eq_u32_e32 vcc, v0, v1
	s_and_saveexec_b64 s[10:11], vcc
	s_cbranch_execz .LBB0_82
	s_mov_b32 s14, 1
	s_mov_b64 s[22:23], 0
	v_mov_b32_e32 v0, 0
	s_branch .LBB0_73

.LBB0_82:
	s_or_b64 exec, exec, s[10:11]
	s_waitcnt vmcnt(0)
	s_waitcnt vmcnt(0)

.LBB0_100:
	s_or_b64 exec, exec, s[4:5]
	s_mov_b64 s[4:5], exec
	v_mbcnt_lo_u32_b32 v0, s4, 0
	v_mbcnt_hi_u32_b32 v0, s5, v0
	v_cmp_eq_u32_e32 vcc, 0, v0
	s_waitcnt vmcnt(0)
	s_and_saveexec_b64 s[8:9], vcc
	s_cbranch_execz .LBB0_102
	s_bcnt1_i32_b64 s4, s[4:5]
	v_mov_b32_e32 v0, 0x2000
	v_mov_b32_e32 v1, s4
	global_atomic_add v0, v1, s[6:7] offset:1024
.LBB0_102:
	s_or_b64 exec, exec, s[8:9]
	buffer_inv sc1
	s_waitcnt vmcnt(0)

.LBB0_150:
	s_or_b64 exec, exec, s[10:11]
	v_cvt_f32_u32_e32 v4, v2
	s_waitcnt vmcnt(0)
	v_readfirstlane_b32 s8, v3
	v_sub_u32_e32 v3, 0, v2
	v_rcp_iflag_f32_e32 v4, v4
	v_add_u32_e32 v5, s8, v1
	v_mul_f32_e32 v4, 0x4f7ffffe, v4
	v_cvt_u32_f32_e32 v4, v4
	v_mul_lo_u32 v1, v3, v4
	v_mul_hi_u32 v1, v4, v1
	v_add_u32_e32 v1, v4, v1
	v_mul_hi_u32 v1, v5, v1
	v_mul_lo_u32 v3, v1, v2
	v_sub_u32_e32 v3, v5, v3
	v_add_u32_e32 v4, 1, v1
	v_cmp_ge_u32_e32 vcc, v3, v2
	s_nop 1
	v_cndmask_b32_e32 v1, v1, v4, vcc
	v_sub_u32_e32 v4, v3, v2
	v_cndmask_b32_e32 v3, v3, v4, vcc
	v_add_u32_e32 v4, 1, v1
	v_cmp_ge_u32_e32 vcc, v3, v2
	v_add_u32_e32 v3, 1, v5
	s_nop 0
	v_cndmask_b32_e32 v1, v1, v4, vcc
	v_mul_lo_u32 v4, v2, v1
	v_add_u32_e32 v2, v4, v2
	v_cmp_ne_u32_e32 vcc, v3, v2
	s_and_saveexec_b64 s[8:9], vcc
	s_xor_b64 s[8:9], exec, s[8:9]
	s_cbranch_execz .LBB0_164
	s_waitcnt lgkmcnt(0)
	buffer_inv sc1
	v_mov_b32_e32 v0, 0x2000
	global_load_dword v0, v0, s[6:7] offset:1024 sc1
	s_add_u32 s12, s6, 0x2400
	s_addc_u32 s13, s7, 0
	s_waitcnt vmcnt(0)
	v_cmp_eq_u32_e32 vcc, v0, v1
	s_and_saveexec_b64 s[10:11], vcc
	s_cbranch_execz .LBB0_163
	s_mov_b32 s17, 1
	s_mov_b64 s[14:15], 0
	v_mov_b32_e32 v0, 0
	s_branch .LBB0_154

.Lip_sum_done:
	s_waitcnt lgkmcnt(0)
	s_barrier
	s_cmpk_lt_i32 s33, 0x100
	s_cbranch_scc1 .Lsig_skip
	s_cmp_lg_u32 s3, 0
	s_cbranch_scc1 .Lsig_skip
	s_mov_b64 s[92:93], exec
	s_mov_b64 exec, 1
	s_and_b32 s90, s85, 7
	s_lshl_b32 s90, s90, 8
	s_add_i32 s91, s90, 0xb8fc4c0
	v_mov_b32_e32 v50, s91
	v_mov_b32_e32 v51, 1
	global_atomic_add v50, v51, s[28:29]
	s_cmpk_ge_i32 s33, 0x190
	s_cbranch_scc1 .Lsig_noctx
	s_add_i32 s90, s90, 0xb8fc480
	v_mov_b32_e32 v52, s90
	global_atomic_add v52, v51, s[28:29]
.Lsig_noctx:
	s_mov_b64 exec, s[92:93]

.LBB0_202:
	s_or_b64 exec, exec, s[54:55]
	s_lshr_b32 s13, s12, 6
	s_or_b32 s13, s13, s86
	v_lshlrev_b32_e32 v198, 3, v148
	s_lshl_b32 s23, s13, 8
	v_cmp_gt_i32_e32 vcc, s22, v152
	v_lshl_add_u64 v[156:157], s[6:7], 0, v[198:199]
	v_or_b32_e32 v144, s23, v167
	v_cndmask_b32_e32 v154, 1.0, v249, vcc
	v_lshlrev_b32_e32 v151, 2, v148
	v_and_b32_e32 v161, 64, v149
	v_mad_i64_i32 v[164:165], s[54:55], v150, s62, v[156:157]
	v_ashrrev_i32_e32 v145, 31, v144
	v_ashrrev_i32_e32 v153, 31, v152
	v_pk_mul_f32 v[146:147], v[154:155], v[60:61] op_sel_hi:[0,1]
	v_pk_mul_f32 v[148:149], v[154:155], v[62:63] op_sel_hi:[0,1]
	v_lshlrev_b64 v[162:163], 9, v[144:145]
	v_lshl_add_u64 v[144:145], v[152:153], 1, v[164:165]
	v_cvt_pk_bf16_f32 v146, v146, v147
	v_cvt_pk_bf16_f32 v147, v148, v149
	ds_write_b64 v200, v[146:147]
	v_pk_mul_f32 v[146:147], v[154:155], v[52:53] op_sel_hi:[0,1]
	v_pk_mul_f32 v[148:149], v[154:155], v[54:55] op_sel_hi:[0,1]
	v_cvt_pk_bf16_f32 v146, v146, v147
	v_cvt_pk_bf16_f32 v147, v148, v149
	ds_write_b64 v200, v[146:147] offset:32
	v_pk_mul_f32 v[146:147], v[154:155], v[56:57] op_sel_hi:[0,1]
	v_pk_mul_f32 v[148:149], v[154:155], v[58:59] op_sel_hi:[0,1]
	v_cvt_pk_bf16_f32 v146, v146, v147
	v_cvt_pk_bf16_f32 v147, v148, v149
	ds_write_b64 v200, v[146:147] offset:64
	v_pk_mul_f32 v[146:147], v[154:155], v[48:49] op_sel_hi:[0,1]
	v_pk_mul_f32 v[148:149], v[154:155], v[50:51] op_sel_hi:[0,1]
	v_cvt_pk_bf16_f32 v146, v146, v147
	v_cvt_pk_bf16_f32 v147, v148, v149
	ds_write_b64 v200, v[146:147] offset:96
	s_waitcnt lgkmcnt(0)
	ds_read_b128 v[204:207], v201
	ds_read_b128 v[208:211], v201 offset:1152
	v_lshl_add_u64 v[212:213], v[144:145], 0, v[202:203]
	v_lshl_add_u64 v[214:215], v[212:213], 0, s[100:101]
	s_waitcnt lgkmcnt(0)
	global_store_dwordx4 v[212:213], v[204:207], off sc1
	global_store_dwordx4 v[214:215], v[208:211], off sc1
	v_and_b32_e32 v144, 0xffffff00, v152
	v_cmp_eq_u32_e32 vcc, s22, v144
	s_xor_b64 s[54:55], s[52:53], -1
	s_and_b64 s[92:93], s[54:55], vcc
	v_and_b32_e32 v168, 0x280, v152
	v_lshlrev_b32_e32 v150, 2, v161
	v_lshlrev_b32_e32 v148, 2, v151
	s_and_saveexec_b64 s[94:95], s[92:93]
	s_cbranch_execz .LBB0_204
	v_cmp_eq_u32_e32 vcc, s18, v168
	v_mov_b32_e32 v151, v199
	v_mov_b32_e32 v149, v199
	v_cndmask_b32_e32 v198, 0, v250, vcc
	v_lshl_add_u64 v[144:145], s[34:35], 0, v[198:199]
	v_lshl_add_u64 v[144:145], v[144:145], 0, v[162:163]
	v_lshl_add_u64 v[144:145], v[144:145], 0, v[150:151]
	v_lshl_add_u64 v[144:145], v[144:145], 0, v[148:149]
	global_store_dwordx4 v[144:145], v[60:63], off
	global_store_dwordx4 v[144:145], v[52:55], off offset:64
	global_store_dwordx4 v[144:145], v[56:59], off offset:128
	global_store_dwordx4 v[144:145], v[48:51], off offset:192

.LBB0_206:
	s_or_b64 exec, exec, s[52:53]
	v_cmp_gt_i32_e32 vcc, s22, v137
	s_ashr_i32 s89, s88, 31
	v_ashrrev_i32_e32 v159, 31, v158
	v_cndmask_b32_e32 v136, 1.0, v249, vcc
	v_lshl_add_u64 v[138:139], v[158:159], 0, s[88:89]
	v_lshl_add_u64 v[158:159], v[138:139], 1, v[164:165]
	v_pk_mul_f32 v[160:161], v[136:137], v[144:145] op_sel_hi:[0,1]
	v_pk_mul_f32 v[164:165], v[136:137], v[146:147] op_sel_hi:[0,1]
	v_cvt_pk_bf16_f32 v160, v160, v161
	v_cvt_pk_bf16_f32 v161, v164, v165
	ds_write_b64 v200, v[160:161]
	v_pk_mul_f32 v[160:161], v[136:137], v[140:141] op_sel_hi:[0,1]
	v_pk_mul_f32 v[164:165], v[136:137], v[142:143] op_sel_hi:[0,1]
	v_cvt_pk_bf16_f32 v160, v160, v161
	v_cvt_pk_bf16_f32 v161, v164, v165
	ds_write_b64 v200, v[160:161] offset:32
	v_pk_mul_f32 v[160:161], v[136:137], v[132:133] op_sel_hi:[0,1]
	v_pk_mul_f32 v[164:165], v[136:137], v[134:135] op_sel_hi:[0,1]
	v_cvt_pk_bf16_f32 v160, v160, v161
	v_cvt_pk_bf16_f32 v161, v164, v165
	ds_write_b64 v200, v[160:161] offset:64
	v_pk_mul_f32 v[160:161], v[136:137], v[128:129] op_sel_hi:[0,1]
	v_pk_mul_f32 v[164:165], v[136:137], v[130:131] op_sel_hi:[0,1]
	v_and_b32_e32 v149, 0xffffff00, v137
	v_cvt_pk_bf16_f32 v160, v160, v161
	v_cvt_pk_bf16_f32 v161, v164, v165
	v_cmp_eq_u32_e32 vcc, s22, v149
	ds_write_b64 v200, v[160:161] offset:96
	s_waitcnt lgkmcnt(0)
	ds_read_b128 v[204:207], v201
	ds_read_b128 v[208:211], v201 offset:1152
	v_lshl_add_u64 v[212:213], v[158:159], 0, v[202:203]
	v_lshl_add_u64 v[214:215], v[212:213], 0, s[100:101]
	s_waitcnt lgkmcnt(0)
	global_store_dwordx4 v[212:213], v[204:207], off offset:256 sc1
	global_store_dwordx4 v[214:215], v[208:211], off offset:256 sc1
	s_and_b64 s[88:89], s[54:55], vcc
	v_and_b32_e32 v158, 0x280, v137
	s_and_saveexec_b64 s[52:53], s[88:89]
	s_cbranch_execz .LBB0_208
	v_cmp_eq_u32_e32 vcc, s18, v158
	v_mov_b32_e32 v151, v199
	v_mov_b32_e32 v149, v199
	v_cndmask_b32_e32 v198, 0, v250, vcc
	v_lshl_add_u64 v[160:161], s[34:35], 0, v[198:199]
	v_lshl_add_u64 v[160:161], v[160:161], 0, v[162:163]
	v_lshl_add_u64 v[160:161], v[160:161], 0, v[150:151]
	v_lshl_add_u64 v[160:161], v[160:161], 0, v[148:149]
	global_store_dwordx4 v[160:161], v[144:147], off
	global_store_dwordx4 v[160:161], v[140:143], off offset:64
	global_store_dwordx4 v[160:161], v[132:135], off offset:128
	global_store_dwordx4 v[160:161], v[128:131], off offset:192

.LBB0_210:
	s_or_b64 exec, exec, s[52:53]
	v_mov_b32_e32 v155, v154
	v_mad_i64_i32 v[126:127], s[52:53], v137, s62, v[156:157]
	v_pk_mul_f32 v[142:143], v[154:155], v[128:129]
	v_pk_mul_f32 v[144:145], v[154:155], v[130:131]
	v_lshl_add_u64 v[140:141], v[152:153], 1, v[126:127]
	v_cvt_pk_bf16_f32 v142, v142, v143
	v_cvt_pk_bf16_f32 v143, v144, v145
	ds_write_b64 v200, v[142:143]
	v_pk_mul_f32 v[142:143], v[154:155], v[120:121]
	v_pk_mul_f32 v[144:145], v[154:155], v[122:123]
	v_cvt_pk_bf16_f32 v142, v142, v143
	v_cvt_pk_bf16_f32 v143, v144, v145
	ds_write_b64 v200, v[142:143] offset:32
	v_pk_mul_f32 v[142:143], v[154:155], v[116:117]
	v_pk_mul_f32 v[144:145], v[154:155], v[118:119]
	v_or_b32_e32 v124, s23, v133
	v_cvt_pk_bf16_f32 v142, v142, v143
	v_cvt_pk_bf16_f32 v143, v144, v145
	v_ashrrev_i32_e32 v125, 31, v124
	ds_write_b64 v200, v[142:143] offset:64
	v_pk_mul_f32 v[142:143], v[154:155], v[112:113]
	v_pk_mul_f32 v[144:145], v[154:155], v[114:115]
	v_lshlrev_b64 v[124:125], 9, v[124:125]
	v_cvt_pk_bf16_f32 v142, v142, v143
	v_cvt_pk_bf16_f32 v143, v144, v145
	ds_write_b64 v200, v[142:143] offset:96
	s_waitcnt lgkmcnt(0)
	ds_read_b128 v[204:207], v201
	ds_read_b128 v[208:211], v201 offset:1152
	v_lshl_add_u64 v[212:213], v[140:141], 0, v[202:203]
	v_lshl_add_u64 v[214:215], v[212:213], 0, s[100:101]
	s_waitcnt lgkmcnt(0)
	global_store_dwordx4 v[212:213], v[204:207], off sc1
	global_store_dwordx4 v[214:215], v[208:211], off sc1
	s_and_saveexec_b64 s[52:53], s[92:93]
	s_cbranch_execz .LBB0_212
	v_cmp_eq_u32_e32 vcc, s18, v168
	v_mov_b32_e32 v151, v199
	v_mov_b32_e32 v149, v199
	v_cndmask_b32_e32 v198, 0, v250, vcc
	v_lshl_add_u64 v[140:141], s[34:35], 0, v[198:199]
	v_lshl_add_u64 v[140:141], v[140:141], 0, v[124:125]
	v_lshl_add_u64 v[140:141], v[140:141], 0, v[150:151]
	v_lshl_add_u64 v[140:141], v[140:141], 0, v[148:149]
	global_store_dwordx4 v[140:141], v[128:131], off
	global_store_dwordx4 v[140:141], v[120:123], off offset:64
	global_store_dwordx4 v[140:141], v[116:119], off offset:128
	global_store_dwordx4 v[140:141], v[112:115], off offset:192

.LBB0_214:
	s_or_b64 exec, exec, s[52:53]
	v_mov_b32_e32 v137, v136
	v_pk_mul_f32 v[110:111], v[136:137], v[112:113]
	v_pk_mul_f32 v[116:117], v[136:137], v[114:115]
	v_lshl_add_u64 v[108:109], v[138:139], 1, v[126:127]
	v_cvt_pk_bf16_f32 v110, v110, v111
	v_cvt_pk_bf16_f32 v111, v116, v117
	ds_write_b64 v200, v[110:111]
	v_pk_mul_f32 v[110:111], v[136:137], v[104:105]
	v_pk_mul_f32 v[116:117], v[136:137], v[106:107]
	v_cvt_pk_bf16_f32 v110, v110, v111
	v_cvt_pk_bf16_f32 v111, v116, v117
	ds_write_b64 v200, v[110:111] offset:32
	v_pk_mul_f32 v[110:111], v[136:137], v[100:101]
	v_pk_mul_f32 v[116:117], v[136:137], v[102:103]
	v_cvt_pk_bf16_f32 v110, v110, v111
	v_cvt_pk_bf16_f32 v111, v116, v117
	ds_write_b64 v200, v[110:111] offset:64
	v_pk_mul_f32 v[110:111], v[136:137], v[96:97]
	v_pk_mul_f32 v[116:117], v[136:137], v[98:99]
	v_cvt_pk_bf16_f32 v110, v110, v111
	v_cvt_pk_bf16_f32 v111, v116, v117
	ds_write_b64 v200, v[110:111] offset:96
	s_waitcnt lgkmcnt(0)
	ds_read_b128 v[204:207], v201
	ds_read_b128 v[208:211], v201 offset:1152
	v_lshl_add_u64 v[212:213], v[108:109], 0, v[202:203]
	v_lshl_add_u64 v[214:215], v[212:213], 0, s[100:101]
	s_waitcnt lgkmcnt(0)
	global_store_dwordx4 v[212:213], v[204:207], off offset:256 sc1
	global_store_dwordx4 v[214:215], v[208:211], off offset:256 sc1
	s_and_saveexec_b64 s[52:53], s[88:89]
	s_cbranch_execz .LBB0_216
	v_cmp_eq_u32_e32 vcc, s18, v158
	v_mov_b32_e32 v151, v199
	v_mov_b32_e32 v149, v199
	v_cndmask_b32_e32 v198, 0, v250, vcc
	v_lshl_add_u64 v[108:109], s[34:35], 0, v[198:199]
	v_lshl_add_u64 v[108:109], v[108:109], 0, v[124:125]
	v_lshl_add_u64 v[108:109], v[108:109], 0, v[150:151]
	v_lshl_add_u64 v[108:109], v[108:109], 0, v[148:149]
	global_store_dwordx4 v[108:109], v[112:115], off
	global_store_dwordx4 v[108:109], v[104:107], off offset:64
	global_store_dwordx4 v[108:109], v[100:103], off offset:128
	global_store_dwordx4 v[108:109], v[96:99], off offset:192

.LBB0_218:
	s_or_b64 exec, exec, s[52:53]
	v_mad_i64_i32 v[94:95], s[52:53], v103, s62, v[156:157]
	v_pk_mul_f32 v[106:107], v[154:155], v[96:97]
	v_pk_mul_f32 v[108:109], v[154:155], v[98:99]
	v_lshl_add_u64 v[104:105], v[152:153], 1, v[94:95]
	v_cvt_pk_bf16_f32 v106, v106, v107
	v_cvt_pk_bf16_f32 v107, v108, v109
	ds_write_b64 v200, v[106:107]
	v_pk_mul_f32 v[106:107], v[154:155], v[88:89]
	v_pk_mul_f32 v[108:109], v[154:155], v[90:91]
	v_cvt_pk_bf16_f32 v106, v106, v107
	v_cvt_pk_bf16_f32 v107, v108, v109
	ds_write_b64 v200, v[106:107] offset:32
	v_pk_mul_f32 v[106:107], v[154:155], v[84:85]
	v_pk_mul_f32 v[108:109], v[154:155], v[86:87]
	v_or_b32_e32 v92, s23, v101
	v_cvt_pk_bf16_f32 v106, v106, v107
	v_cvt_pk_bf16_f32 v107, v108, v109
	v_ashrrev_i32_e32 v93, 31, v92
	ds_write_b64 v200, v[106:107] offset:64
	v_pk_mul_f32 v[106:107], v[154:155], v[80:81]
	v_pk_mul_f32 v[108:109], v[154:155], v[82:83]
	v_lshlrev_b64 v[92:93], 9, v[92:93]
	v_cvt_pk_bf16_f32 v106, v106, v107
	v_cvt_pk_bf16_f32 v107, v108, v109
	ds_write_b64 v200, v[106:107] offset:96
	s_waitcnt lgkmcnt(0)
	ds_read_b128 v[204:207], v201
	ds_read_b128 v[208:211], v201 offset:1152
	v_lshl_add_u64 v[212:213], v[104:105], 0, v[202:203]
	v_lshl_add_u64 v[214:215], v[212:213], 0, s[100:101]
	s_waitcnt lgkmcnt(0)
	global_store_dwordx4 v[212:213], v[204:207], off sc1
	global_store_dwordx4 v[214:215], v[208:211], off sc1
	s_and_saveexec_b64 s[52:53], s[92:93]
	s_cbranch_execz .LBB0_220
	v_cmp_eq_u32_e32 vcc, s18, v168
	v_mov_b32_e32 v151, v199
	v_mov_b32_e32 v149, v199
	v_cndmask_b32_e32 v198, 0, v250, vcc
	v_lshl_add_u64 v[104:105], s[34:35], 0, v[198:199]
	v_lshl_add_u64 v[104:105], v[104:105], 0, v[92:93]
	v_lshl_add_u64 v[104:105], v[104:105], 0, v[150:151]
	v_lshl_add_u64 v[104:105], v[104:105], 0, v[148:149]
	global_store_dwordx4 v[104:105], v[96:99], off
	global_store_dwordx4 v[104:105], v[88:91], off offset:64
	global_store_dwordx4 v[104:105], v[84:87], off offset:128
	global_store_dwordx4 v[104:105], v[80:83], off offset:192

.LBB0_222:
	s_or_b64 exec, exec, s[52:53]
	v_pk_mul_f32 v[78:79], v[136:137], v[80:81]
	v_pk_mul_f32 v[84:85], v[136:137], v[82:83]
	v_lshl_add_u64 v[76:77], v[138:139], 1, v[94:95]
	v_cvt_pk_bf16_f32 v78, v78, v79
	v_cvt_pk_bf16_f32 v79, v84, v85
	ds_write_b64 v200, v[78:79]
	v_pk_mul_f32 v[78:79], v[136:137], v[72:73]
	v_pk_mul_f32 v[84:85], v[136:137], v[74:75]
	v_cvt_pk_bf16_f32 v78, v78, v79
	v_cvt_pk_bf16_f32 v79, v84, v85
	ds_write_b64 v200, v[78:79] offset:32
	v_pk_mul_f32 v[78:79], v[136:137], v[68:69]
	v_pk_mul_f32 v[84:85], v[136:137], v[70:71]
	v_cvt_pk_bf16_f32 v78, v78, v79
	v_cvt_pk_bf16_f32 v79, v84, v85
	ds_write_b64 v200, v[78:79] offset:64
	v_pk_mul_f32 v[78:79], v[136:137], v[64:65]
	v_pk_mul_f32 v[84:85], v[136:137], v[66:67]
	v_cvt_pk_bf16_f32 v78, v78, v79
	v_cvt_pk_bf16_f32 v79, v84, v85
	ds_write_b64 v200, v[78:79] offset:96
	s_waitcnt lgkmcnt(0)
	ds_read_b128 v[204:207], v201
	ds_read_b128 v[208:211], v201 offset:1152
	v_lshl_add_u64 v[212:213], v[76:77], 0, v[202:203]
	v_lshl_add_u64 v[214:215], v[212:213], 0, s[100:101]
	s_waitcnt lgkmcnt(0)
	global_store_dwordx4 v[212:213], v[204:207], off offset:256 sc1
	global_store_dwordx4 v[214:215], v[208:211], off offset:256 sc1
	s_and_saveexec_b64 s[52:53], s[88:89]
	s_cbranch_execz .LBB0_224
	v_cmp_eq_u32_e32 vcc, s18, v158
	v_mov_b32_e32 v151, v199
	v_mov_b32_e32 v149, v199
	v_cndmask_b32_e32 v198, 0, v250, vcc
	v_lshl_add_u64 v[76:77], s[34:35], 0, v[198:199]
	v_lshl_add_u64 v[76:77], v[76:77], 0, v[92:93]
	v_lshl_add_u64 v[76:77], v[76:77], 0, v[150:151]
	v_lshl_add_u64 v[76:77], v[76:77], 0, v[148:149]
	global_store_dwordx4 v[76:77], v[80:83], off
	global_store_dwordx4 v[76:77], v[72:75], off offset:64
	global_store_dwordx4 v[76:77], v[68:71], off offset:128
	global_store_dwordx4 v[76:77], v[64:67], off offset:192

.LBB0_226:
	s_or_b64 exec, exec, s[12:13]
	v_mad_i64_i32 v[30:31], s[12:13], v66, s62, v[156:157]
	v_pk_mul_f32 v[40:41], v[154:155], v[32:33]
	v_pk_mul_f32 v[42:43], v[154:155], v[34:35]
	v_lshl_add_u64 v[38:39], v[152:153], 1, v[30:31]
	v_cvt_pk_bf16_f32 v40, v40, v41
	v_cvt_pk_bf16_f32 v41, v42, v43
	ds_write_b64 v200, v[40:41]
	v_pk_mul_f32 v[40:41], v[154:155], v[24:25]
	v_pk_mul_f32 v[42:43], v[154:155], v[26:27]
	v_cvt_pk_bf16_f32 v40, v40, v41
	v_cvt_pk_bf16_f32 v41, v42, v43
	ds_write_b64 v200, v[40:41] offset:32
	v_pk_mul_f32 v[40:41], v[154:155], v[20:21]
	v_pk_mul_f32 v[42:43], v[154:155], v[22:23]
	v_or_b32_e32 v28, s23, v65
	v_cvt_pk_bf16_f32 v40, v40, v41
	v_cvt_pk_bf16_f32 v41, v42, v43
	v_ashrrev_i32_e32 v29, 31, v28
	ds_write_b64 v200, v[40:41] offset:64
	v_pk_mul_f32 v[40:41], v[154:155], v[16:17]
	v_pk_mul_f32 v[42:43], v[154:155], v[18:19]
	v_lshlrev_b64 v[28:29], 9, v[28:29]
	v_cvt_pk_bf16_f32 v40, v40, v41
	v_cvt_pk_bf16_f32 v41, v42, v43
	ds_write_b64 v200, v[40:41] offset:96
	s_waitcnt lgkmcnt(0)
	ds_read_b128 v[204:207], v201
	ds_read_b128 v[208:211], v201 offset:1152
	v_lshl_add_u64 v[212:213], v[38:39], 0, v[202:203]
	v_lshl_add_u64 v[214:215], v[212:213], 0, s[100:101]
	s_waitcnt lgkmcnt(0)
	global_store_dwordx4 v[212:213], v[204:207], off sc1
	global_store_dwordx4 v[214:215], v[208:211], off sc1
	s_and_saveexec_b64 s[12:13], s[92:93]
	s_cbranch_execz .LBB0_228
	v_cmp_eq_u32_e32 vcc, s18, v168
	v_mov_b32_e32 v151, v199
	v_mov_b32_e32 v149, v199
	v_cndmask_b32_e32 v198, 0, v250, vcc
	v_lshl_add_u64 v[38:39], s[34:35], 0, v[198:199]
	v_lshl_add_u64 v[38:39], v[38:39], 0, v[28:29]
	v_lshl_add_u64 v[38:39], v[38:39], 0, v[150:151]
	v_lshl_add_u64 v[38:39], v[38:39], 0, v[148:149]
	global_store_dwordx4 v[38:39], v[32:35], off
	global_store_dwordx4 v[38:39], v[24:27], off offset:64
	global_store_dwordx4 v[38:39], v[20:23], off offset:128
	global_store_dwordx4 v[38:39], v[16:19], off offset:192

.LBB0_230:
	s_or_b64 exec, exec, s[12:13]
	v_pk_mul_f32 v[14:15], v[136:137], v[16:17]
	v_pk_mul_f32 v[20:21], v[136:137], v[18:19]
	v_lshl_add_u64 v[12:13], v[138:139], 1, v[30:31]
	v_cvt_pk_bf16_f32 v14, v14, v15
	v_cvt_pk_bf16_f32 v15, v20, v21
	ds_write_b64 v200, v[14:15]
	v_pk_mul_f32 v[14:15], v[136:137], v[8:9]
	v_pk_mul_f32 v[20:21], v[136:137], v[10:11]
	v_cvt_pk_bf16_f32 v14, v14, v15
	v_cvt_pk_bf16_f32 v15, v20, v21
	ds_write_b64 v200, v[14:15] offset:32
	v_pk_mul_f32 v[14:15], v[136:137], v[4:5]
	v_pk_mul_f32 v[20:21], v[136:137], v[6:7]
	v_cvt_pk_bf16_f32 v14, v14, v15
	v_cvt_pk_bf16_f32 v15, v20, v21
	ds_write_b64 v200, v[14:15] offset:64
	v_pk_mul_f32 v[14:15], v[136:137], v[0:1]
	v_pk_mul_f32 v[20:21], v[136:137], v[2:3]
	v_cvt_pk_bf16_f32 v14, v14, v15
	v_cvt_pk_bf16_f32 v15, v20, v21
	ds_write_b64 v200, v[14:15] offset:96
	s_waitcnt lgkmcnt(0)
	ds_read_b128 v[204:207], v201
	ds_read_b128 v[208:211], v201 offset:1152
	v_lshl_add_u64 v[212:213], v[12:13], 0, v[202:203]
	v_lshl_add_u64 v[214:215], v[212:213], 0, s[100:101]
	s_waitcnt lgkmcnt(0)
	global_store_dwordx4 v[212:213], v[204:207], off offset:256 sc1
	global_store_dwordx4 v[214:215], v[208:211], off offset:256 sc1
	s_and_saveexec_b64 s[12:13], s[88:89]
	s_cbranch_execz .LBB0_189
	v_cmp_eq_u32_e32 vcc, s18, v158
	v_mov_b32_e32 v151, v199
	v_mov_b32_e32 v149, v199
	v_cndmask_b32_e32 v198, 0, v250, vcc
	v_lshl_add_u64 v[12:13], s[34:35], 0, v[198:199]
	v_lshl_add_u64 v[12:13], v[12:13], 0, v[28:29]
	v_lshl_add_u64 v[12:13], v[12:13], 0, v[150:151]
	v_lshl_add_u64 v[12:13], v[12:13], 0, v[148:149]
	global_store_dwordx4 v[12:13], v[16:19], off
	global_store_dwordx4 v[12:13], v[8:11], off offset:64
	global_store_dwordx4 v[12:13], v[4:7], off offset:128
	global_store_dwordx4 v[12:13], v[0:3], off offset:192
	s_branch .LBB0_189
.LBB0_232:
	v_mov_b32_e32 v0, 0x23808
	ds_read_b32 v0, v0
	s_waitcnt lgkmcnt(0)
	v_readfirstlane_b32 s98, v0
	s_cmp_eq_u32 s98, 0
	s_cbranch_scc1 .Lemi_skip
	s_waitcnt vmcnt(0)
	s_barrier
	s_cmp_lg_u32 s3, 0
	s_cbranch_scc1 .Ltc_nosig
	s_mov_b64 s[10:11], exec
	s_mov_b64 exec, 1
	s_and_b32 s4, s85, 7
	s_lshl_b32 s4, s4, 8
	s_add_i32 s4, s4, 0xb8fc4c0
	v_mov_b32_e32 v0, s4
	v_mov_b32_e32 v1, 1
	global_atomic_add v0, v1, s[28:29]
	s_mov_b64 exec, s[10:11]
.Ltc_nosig:
	s_cmpk_lt_i32 s85, 0xb0
	s_cbranch_scc1 .Lemi_skip
	s_waitcnt vmcnt(0)
	s_cmp_lg_u32 s3, 0
	s_cbranch_scc1 .Lemi_nopoll
	s_mov_b64 s[10:11], exec
	s_mov_b64 exec, 1
	s_and_b32 s4, s85, 7
	s_lshl_b32 s4, s4, 8
	s_add_i32 s4, s4, 0xb8fc480
	v_mov_b32_e32 v0, s4
	s_add_i32 s5, s86, 1
	s_mul_i32 s5, s5, 18
	v_mov_b32_e32 v1, s5
	s_mov_b32 s6, 0
	buffer_inv sc1

.Lemi_got:
	s_waitcnt vmcnt(0)
	s_mov_b64 exec, s[10:11]

.Lemi_skip:
	s_mov_b64 s[4:5], 0xb8fb000
	s_getreg_b32 s6, hwreg(HW_REG_XCC_ID, 0, 4)
	v_mbcnt_lo_u32_b32 v0, -1, 0
	v_mbcnt_hi_u32_b32 v0, -1, v0
	s_waitcnt vmcnt(0)
	s_waitcnt lgkmcnt(0)
	v_sub_u32_e32 v0, 0, v0
	v_cmp_eq_u32_e32 vcc, s3, v0
	s_barrier
	s_and_saveexec_b64 s[0:1], vcc
	s_cbranch_execz .LBB0_284
	v_mov_b32_e32 v1, 0x23808
	ds_read_b32 v1, v1
	s_waitcnt lgkmcnt(0)
	v_readfirstlane_b32 s7, v1
	s_cmp_eq_u32 s7, 0
	s_cbranch_scc1 .Ltc_global
	buffer_inv sc1
	s_and_b32 s8, s85, 7
	s_add_i32 s9, s86, 1
	s_mul_i32 s9, s9, 54
	v_mov_b32_e32 v4, s9
	s_lshl_b32 s10, s8, 8
	s_add_i32 s10, s10, 0xb8fc4c0
	v_mov_b32_e32 v2, s10
	s_add_i32 s10, s8, 1
	s_and_b32 s10, s10, 7
	s_lshl_b32 s10, s10, 8
	s_add_i32 s10, s10, 0xb8fc4c0
	v_mov_b32_e32 v3, s10
	s_add_i32 s10, s8, 7
	s_and_b32 s10, s10, 7
	s_lshl_b32 s10, s10, 8
	s_add_i32 s10, s10, 0xb8fc4c0
	v_mov_b32_e32 v9, s10
	s_mov_b32 s11, 0
.Ltc_spin:
	global_load_dword v5, v2, s[28:29] sc1
	global_load_dword v6, v3, s[28:29] sc1
	global_load_dword v7, v9, s[28:29] sc1
	s_waitcnt vmcnt(0)
	v_min_u32_e32 v5, v5, v6
	v_min_u32_e32 v5, v5, v7
	v_cmp_ge_u32_e32 vcc, v5, v4
	s_cbranch_vccnz .Ltc_got
	s_sleep 1
	s_add_i32 s11, s11, 1
	s_cmp_lt_u32 s11, 0x8000
	s_cbranch_scc1 .Ltc_spin
.Ltc_got:
	s_waitcnt vmcnt(0)
	s_branch .LBB0_284

.LBB0_250:
	s_or_b64 exec, exec, s[10:11]
	v_cvt_f32_u32_e32 v4, v2
	s_waitcnt vmcnt(0)
	v_readfirstlane_b32 s8, v3
	v_sub_u32_e32 v3, 0, v2
	v_rcp_iflag_f32_e32 v4, v4
	v_add_u32_e32 v5, s8, v1
	v_mul_f32_e32 v4, 0x4f7ffffe, v4
	v_cvt_u32_f32_e32 v4, v4
	v_mul_lo_u32 v1, v3, v4
	v_mul_hi_u32 v1, v4, v1
	v_add_u32_e32 v1, v4, v1
	v_mul_hi_u32 v1, v5, v1
	v_mul_lo_u32 v3, v1, v2
	v_sub_u32_e32 v3, v5, v3
	v_add_u32_e32 v4, 1, v1
	v_cmp_ge_u32_e32 vcc, v3, v2
	s_nop 1
	v_cndmask_b32_e32 v1, v1, v4, vcc
	v_sub_u32_e32 v4, v3, v2
	v_cndmask_b32_e32 v3, v3, v4, vcc
	v_add_u32_e32 v4, 1, v1
	v_cmp_ge_u32_e32 vcc, v3, v2
	v_add_u32_e32 v3, 1, v5
	s_nop 0
	v_cndmask_b32_e32 v1, v1, v4, vcc
	v_mul_lo_u32 v4, v2, v1
	v_add_u32_e32 v2, v4, v2
	v_cmp_ne_u32_e32 vcc, v3, v2
	s_and_saveexec_b64 s[8:9], vcc
	s_xor_b64 s[8:9], exec, s[8:9]
	s_cbranch_execz .LBB0_264
	s_waitcnt lgkmcnt(0)
	buffer_inv sc1
	v_mov_b32_e32 v0, 0x2000
	global_load_dword v0, v0, s[6:7] offset:1024 sc1
	s_add_u32 s12, s6, 0x2400
	s_addc_u32 s13, s7, 0
	s_waitcnt vmcnt(0)
	v_cmp_eq_u32_e32 vcc, v0, v1
	s_and_saveexec_b64 s[10:11], vcc
	s_cbranch_execz .LBB0_263
	s_mov_b32 s19, 1
	s_mov_b64 s[52:53], 0
	s_branch .LBB0_254

.LBB0_281:
	s_or_b64 exec, exec, s[4:5]
	s_mov_b64 s[4:5], exec
	v_mbcnt_lo_u32_b32 v0, s4, 0
	v_mbcnt_hi_u32_b32 v0, s5, v0
	v_cmp_eq_u32_e32 vcc, 0, v0
	s_waitcnt vmcnt(0)
	s_and_saveexec_b64 s[8:9], vcc
	s_cbranch_execz .LBB0_283
	s_bcnt1_i32_b64 s4, s[4:5]
	v_mov_b32_e32 v0, s4
	v_mov_b32_e32 v1, 0x2000
	global_atomic_add v1, v0, s[6:7] offset:1024

.LBB0_406:
	s_or_b64 exec, exec, s[10:11]
	s_lshl_b32 s12, s86, 17
	v_readlane_b32 s13, v254, 54
	s_or_b32 s12, s12, s13
	s_add_u32 s13, s28, s54
	s_addc_u32 s68, s29, s55
	s_add_u32 s12, s13, s12
	s_addc_u32 s13, s68, 0
	v_lshlrev_b32_e32 v124, 3, v21
	v_and_b32_e32 v126, 0xffffff80, v124
	v_lshl_add_u64 v[124:125], s[12:13], 0, v[198:199]
	v_ashrrev_i32_e32 v127, 31, v126
	v_lshl_add_u64 v[116:117], v[126:127], 1, v[124:125]
	v_add_u32_e32 v118, 0x1000, v126
	v_ashrrev_i32_e32 v119, 31, v118
	v_lshl_add_u64 v[118:119], v[118:119], 1, v[124:125]
	v_add_u32_e32 v120, 0x2000, v126
	v_ashrrev_i32_e32 v121, 31, v120
	v_lshl_add_u64 v[120:121], v[120:121], 1, v[124:125]
	v_add_u32_e32 v122, 0x3000, v126
	v_ashrrev_i32_e32 v123, 31, v122
	v_lshl_add_u64 v[122:123], v[122:123], 1, v[124:125]
	global_load_dwordx4 v[128:131], v[116:117], off
	global_load_dwordx4 v[32:35], v[118:119], off
	global_load_dwordx4 v[36:39], v[120:121], off
	global_load_dwordx4 v[40:43], v[122:123], off
	v_lshlrev_b32_e32 v20, 4, v132
	v_and_b32_e32 v20, 0xf0, v20
	s_and_saveexec_b64 s[10:11], vcc
	s_cbranch_execnz .LBB0_418
	s_or_b64 exec, exec, s[10:11]
	s_and_saveexec_b64 s[10:11], s[0:1]
	s_cbranch_execnz .LBB0_419

.LBB0_411:
	s_waitcnt vmcnt(4)
	v_mad_u64_u32 v[0:1], s[4:5], v26, s66, v[20:21]
	ds_write_b128 v0, v[16:19]
.LBB0_412:
	s_or_b64 exec, exec, s[0:1]
	v_mad_u64_u32 v[14:15], s[0:1], v22, s66, v[20:21]
	v_mad_u64_u32 v[6:7], s[0:1], v23, s66, v[20:21]
	v_lshrrev_b32_e32 v0, 1, v21
	v_and_b32_e32 v1, 31, v132
	v_ashrrev_i32_e32 v96, 8, v21
	v_and_b32_e32 v119, 0x60, v0
	v_readlane_b32 s36, v254, 0
	v_lshlrev_b32_e32 v123, 6, v96
	v_readlane_b32 s48, v254, 12
	v_readlane_b32 s49, v254, 13
	v_bfe_u32 v97, v132, 5, 1
	v_readlane_b32 s40, v254, 4
	v_readlane_b32 s41, v254, 5
	s_mov_b64 s[12:13], s[48:49]
	v_readlane_b32 s42, v254, 6
	v_readlane_b32 s43, v254, 7
	v_readlane_b32 s44, v254, 8
	v_readlane_b32 s45, v254, 9
	s_mov_b64 s[4:5], s[40:41]
	s_mov_b64 s[8:9], s[44:45]
	v_ashrrev_i32_e32 v135, 2, v21
	v_and_b32_e32 v134, -16, v135
	v_mul_lo_u32 v133, v134, s66
	v_readlane_b32 s37, v254, 1
	v_readlane_b32 s38, v254, 2
	v_readlane_b32 s39, v254, 3
	v_readlane_b32 s46, v254, 10
	v_readlane_b32 s47, v254, 11
	v_readlane_b32 s50, v254, 14
	v_readlane_b32 s51, v254, 15
	s_mov_b64 s[6:7], s[42:43]
	s_waitcnt vmcnt(3)
	ds_write_b128 v14, v[128:131] offset:39168
	s_waitcnt vmcnt(2)
	ds_write_b128 v6, v[32:35] offset:39168
	v_mad_u64_u32 v[6:7], s[0:1], v24, s66, v[20:21]
	s_waitcnt vmcnt(1)
	ds_write_b128 v6, v[36:39] offset:39168
	v_mad_u64_u32 v[6:7], s[0:1], v25, s66, v[20:21]
	v_readlane_b32 s0, v254, 52
	s_waitcnt vmcnt(0)
	ds_write_b128 v6, v[40:43] offset:39168
	v_or3_b32 v198, v1, s0, v119
	v_readlane_b32 s0, v254, 57
	v_mov_b64_e32 v[2:3], s[52:53]
	s_nop 0
	v_add_u32_e32 v0, s0, v123
	v_mad_u64_u32 v[2:3], s[0:1], v198, s62, v[2:3]
	v_lshl_or_b32 v112, v97, 2, v0
	s_add_u32 s0, s12, s88
	s_addc_u32 s1, s13, s89
	v_ashrrev_i32_e32 v113, 31, v112
	s_add_u32 s4, s8, s88
	v_lshlrev_b64 v[4:5], 2, v[112:113]
	s_addc_u32 s5, s9, s89
	v_lshl_add_u64 v[2:3], v[112:113], 1, v[2:3]
	v_lshl_add_u64 v[6:7], s[0:1], 0, v[4:5]
	global_load_dwordx2 v[114:115], v[2:3], off offset:3584
	v_lshl_add_u64 v[4:5], s[4:5], 0, v[4:5]
	global_load_dwordx4 v[92:95], v[6:7], off
	global_load_dwordx4 v[88:91], v[4:5], off
	global_load_dwordx2 v[110:111], v[2:3], off offset:3600
	global_load_dwordx4 v[84:87], v[6:7], off offset:32
	global_load_dwordx4 v[80:83], v[4:5], off offset:32
	global_load_dwordx2 v[108:109], v[2:3], off offset:3616
	global_load_dwordx4 v[76:79], v[6:7], off offset:64
	global_load_dwordx4 v[72:75], v[4:5], off offset:64
	global_load_dwordx2 v[106:107], v[2:3], off offset:3632
	global_load_dwordx4 v[68:71], v[6:7], off offset:96
	global_load_dwordx4 v[64:67], v[4:5], off offset:96
	global_load_dwordx2 v[104:105], v[2:3], off offset:3648
	global_load_dwordx4 v[60:63], v[6:7], off offset:128
	global_load_dwordx4 v[56:59], v[4:5], off offset:128
	global_load_dwordx2 v[102:103], v[2:3], off offset:3664
	global_load_dwordx4 v[52:55], v[6:7], off offset:160
	global_load_dwordx4 v[48:51], v[4:5], off offset:160
	global_load_dwordx2 v[100:101], v[2:3], off offset:3680
	global_load_dwordx4 v[44:47], v[6:7], off offset:192
	global_load_dwordx4 v[40:43], v[4:5], off offset:192
	global_load_dwordx2 v[98:99], v[2:3], off offset:3696
	global_load_dwordx4 v[36:39], v[6:7], off offset:224
	global_load_dwordx4 v[32:35], v[4:5], off offset:224
	s_cmp_lt_i32 s96, 2
	s_waitcnt lgkmcnt(0)
	s_barrier
	s_cbranch_scc1 .LBB0_422
	s_cmp_gt_i32 s96, 2
	s_mov_b64 s[0:1], -1
	s_cbranch_scc0 .LBB0_415
	v_lshlrev_b32_e32 v0, 2, v132
	v_and_b32_e32 v129, 0xfc, v0
	v_add_u32_e32 v137, v133, v129
	ds_read2_b32 v[2:3], v137 offset1:68
	ds_read2_b32 v[4:5], v137 offset0:136 offset1:204
	v_readlane_b32 s1, v254, 55
	v_or_b32_e32 v122, 1, v134
	v_readlane_b32 s0, v254, 51
	v_add_u32_e32 v124, s1, v122
	v_max_i32_e32 v125, 8, v124
	v_or_b32_e32 v124, 8, v124
	v_add_u32_e32 v0, 0x400, v137
	v_min_i32_e32 v124, s0, v124
	s_waitcnt lgkmcnt(1)
	v_lshlrev_b32_e32 v28, 16, v2
	v_and_b32_e32 v29, 0xffff0000, v2
	v_lshlrev_b32_e32 v26, 16, v3
	v_and_b32_e32 v27, 0xffff0000, v3
	ds_read2_b32 v[2:3], v0 offset0:16 offset1:84
	v_sub_u32_e32 v124, v124, v125
	v_add_u32_e32 v124, 8, v124
	v_cvt_f32_i32_e32 v126, v124
	s_waitcnt lgkmcnt(1)
	v_lshlrev_b32_e32 v24, 16, v4
	v_and_b32_e32 v25, 0xffff0000, v4
	v_lshlrev_b32_e32 v22, 16, v5
	v_and_b32_e32 v23, 0xffff0000, v5
	ds_read2_b32 v[4:5], v0 offset0:152 offset1:220
	v_add_u32_e32 v0, 0x800, v137
	s_waitcnt lgkmcnt(1)
	v_lshlrev_b32_e32 v30, 16, v2
	v_and_b32_e32 v31, 0xffff0000, v2
	v_lshlrev_b32_e32 v20, 16, v3
	v_and_b32_e32 v21, 0xffff0000, v3
	ds_read2_b32 v[2:3], v0 offset0:32 offset1:100
	v_add_u32_e32 v141, s1, v134
	v_mul_lo_u32 v140, v122, s66
	v_rcp_iflag_f32_e32 v122, v126
	v_add_u32_e32 v126, 2, v141
	v_add_u32_e32 v169, 10, v141
	v_add_u32_e32 v130, 3, v141
	v_add_u32_e32 v173, 11, v141
	v_max_i32_e32 v126, 8, v126
	v_min_i32_e32 v127, s0, v169
	v_max_i32_e32 v130, 8, v130
	v_min_i32_e32 v131, s0, v173
	v_sub_u32_e32 v126, v127, v126
	v_sub_u32_e32 v130, v131, v130
	s_waitcnt lgkmcnt(1)
	v_lshlrev_b32_e32 v18, 16, v4
	v_and_b32_e32 v19, 0xffff0000, v4
	v_lshlrev_b32_e32 v16, 16, v5
	v_and_b32_e32 v17, 0xffff0000, v5
	ds_read2_b32 v[4:5], v0 offset0:168 offset1:236
	v_add_u32_e32 v0, 0xc00, v137
	v_add_u32_e32 v126, 8, v126
	v_add_u32_e32 v130, 8, v130
	s_waitcnt lgkmcnt(1)
	v_lshlrev_b32_e32 v14, 16, v2
	v_and_b32_e32 v15, 0xffff0000, v2
	v_lshlrev_b32_e32 v12, 16, v3
	v_and_b32_e32 v13, 0xffff0000, v3
	ds_read2_b32 v[2:3], v0 offset0:48 offset1:116
	ds_read2_b32 v[116:117], v0 offset0:184 offset1:252
	v_cvt_f32_i32_e32 v128, v126
	v_cvt_f32_i32_e32 v138, v130
	v_add_u32_e32 v181, 12, v141
	s_waitcnt lgkmcnt(2)
	v_lshlrev_b32_e32 v10, 16, v4
	v_rcp_iflag_f32_e32 v136, v128
	v_rcp_iflag_f32_e32 v128, v138
	v_add_u32_e32 v138, 4, v141
	v_and_b32_e32 v11, 0xffff0000, v4
	v_lshlrev_b32_e32 v8, 16, v5
	v_and_b32_e32 v9, 0xffff0000, v5
	s_waitcnt lgkmcnt(1)
	v_lshlrev_b32_e32 v6, 16, v2
	v_and_b32_e32 v7, 0xffff0000, v2
	v_lshlrev_b32_e32 v4, 16, v3
	v_and_b32_e32 v5, 0xffff0000, v3
	s_waitcnt lgkmcnt(0)
	v_lshlrev_b32_e32 v2, 16, v116
	v_and_b32_e32 v3, 0xffff0000, v116
	v_or_b32_e32 v116, 8, v141
	v_max_i32_e32 v138, 8, v138
	v_min_i32_e32 v139, s0, v181
	v_max_i32_e32 v0, 8, v141
	v_min_i32_e32 v116, s0, v116
	v_sub_u32_e32 v138, v139, v138
	v_sub_u32_e32 v0, v116, v0
	v_add_u32_e32 v138, 8, v138
	v_add_u32_e32 v0, 8, v0
	v_cvt_f32_i32_e32 v142, v138
	v_add_u32_e32 v138, 0x1400, v137
	v_cvt_f32_i32_e32 v118, v0
	v_or_b32_e32 v0, 0x12100, v129
	ds_read2_b32 v[138:139], v138 offset0:80 offset1:148
	v_add_u32_e32 v144, 0x330, v140
	v_add_u32_e32 v185, v0, v144
	v_add_u32_e32 v194, v144, v129
	v_add_u32_e32 v144, 6, v141
	v_add_u32_e32 v195, 14, v141
	v_max_i32_e32 v146, 8, v144
	v_min_i32_e32 v147, s0, v195
	v_sub_u32_e32 v146, v147, v146
	v_add_u32_e32 v146, 8, v146
	v_cvt_f32_i32_e32 v148, v146
	s_waitcnt lgkmcnt(0)
	v_lshlrev_b32_e32 v146, 16, v139
	v_and_b32_e32 v147, 0xffff0000, v139
	v_add_u32_e32 v139, 0x1600, v137
	ds_read2_b32 v[152:153], v139 offset0:88 offset1:156
	v_add_u32_e32 v139, 7, v141
	v_add_u32_e32 v151, 15, v141
	v_add_u32_e32 v161, v0, v140
	v_rcp_iflag_f32_e32 v140, v142
	v_lshlrev_b32_e32 v142, 16, v138
	v_and_b32_e32 v143, 0xffff0000, v138
	v_add_u32_e32 v138, 5, v141
	v_add_u32_e32 v187, 13, v141
	v_max_i32_e32 v139, 8, v139
	v_min_i32_e32 v151, s0, v151
	v_max_i32_e32 v138, 8, v138
	v_min_i32_e32 v145, s0, v187
	v_add_u32_e32 v144, 0x800, v194
	v_sub_u32_e32 v139, v151, v139
	v_sub_u32_e32 v138, v145, v138
	ds_read2_b32 v[144:145], v144 offset0:168 offset1:236
	v_add_u32_e32 v139, 8, v139
	v_cvt_f32_i32_e32 v139, v139
	s_waitcnt lgkmcnt(1)
	v_lshlrev_b32_e32 v154, 16, v152
	v_and_b32_e32 v155, 0xffff0000, v152
	s_waitcnt lgkmcnt(0)
	v_lshlrev_b32_e32 v150, 16, v144
	v_and_b32_e32 v151, 0xffff0000, v144
	v_rcp_iflag_f32_e32 v144, v139
	v_add_u32_e32 v139, 8, v141
	v_add_u32_e32 v152, 16, v141
	v_max_i32_e32 v139, 8, v139
	v_min_i32_e32 v152, s0, v152
	v_sub_u32_e32 v139, v152, v139
	v_add_u32_e32 v139, 8, v139
	v_cvt_f32_i32_e32 v139, v139
	v_lshlrev_b32_e32 v156, 16, v145
	v_and_b32_e32 v157, 0xffff0000, v145
	v_add_u32_e32 v145, 17, v141
	v_rcp_iflag_f32_e32 v160, v139
	v_add_u32_e32 v139, 0x1800, v137
	ds_read2_b32 v[164:165], v139 offset0:96 offset1:164
	v_add_u32_e32 v139, 9, v141
	v_max_i32_e32 v139, 8, v139
	v_min_i32_e32 v145, s0, v145
	v_add_u32_e32 v170, 0xc00, v194
	v_sub_u32_e32 v139, v145, v139
	ds_read2_b32 v[158:159], v170 offset0:48 offset1:116
	v_add_u32_e32 v139, 8, v139
	v_cvt_f32_i32_e32 v139, v139
	v_add_u32_e32 v145, 18, v141
	v_min_i32_e32 v145, s0, v145
	s_waitcnt lgkmcnt(0)
	v_lshlrev_b32_e32 v162, 16, v158
	v_and_b32_e32 v163, 0xffff0000, v158
	v_rcp_iflag_f32_e32 v158, v139
	v_max_i32_e32 v139, 8, v169
	v_sub_u32_e32 v139, v145, v139
	v_add_u32_e32 v139, 8, v139
	v_cvt_f32_i32_e32 v139, v139
	v_add_u32_e32 v145, 19, v141
	v_min_i32_e32 v145, s0, v145
	ds_read2_b32 v[170:171], v170 offset0:184 offset1:252
	v_rcp_iflag_f32_e32 v172, v139
	v_add_u32_e32 v139, 0x1a00, v137
	ds_read2_b32 v[176:177], v139 offset0:104 offset1:172
	v_max_i32_e32 v139, 8, v173
	v_sub_u32_e32 v139, v145, v139
	v_add_u32_e32 v139, 8, v139
	v_cvt_f32_i32_e32 v139, v139
	v_pk_add_f32 v[204:205], v[28:29], 0 op_sel_hi:[1,0]
	v_add_u32_e32 v145, 20, v141
	v_pk_add_f32 v[204:205], v[204:205], v[26:27]
	s_waitcnt lgkmcnt(1)
	v_lshlrev_b32_e32 v174, 16, v170
	v_pk_add_f32 v[204:205], v[204:205], v[24:25]
	v_and_b32_e32 v175, 0xffff0000, v170
	v_pk_add_f32 v[204:205], v[204:205], v[22:23]
	v_rcp_iflag_f32_e32 v170, v139
	v_max_i32_e32 v139, 8, v181
	v_min_i32_e32 v145, s0, v145
	v_pk_add_f32 v[204:205], v[204:205], v[30:31]
	v_sub_u32_e32 v139, v145, v139
	v_pk_add_f32 v[204:205], v[204:205], v[20:21]
	v_add_u32_e32 v139, 8, v139
	v_pk_add_f32 v[30:31], v[142:143], v[30:31] neg_lo:[0,1] neg_hi:[0,1]
	v_pk_add_f32 v[142:143], v[204:205], v[18:19]
	v_cvt_f32_i32_e32 v139, v139
	v_pk_add_f32 v[142:143], v[142:143], v[16:17]
	v_add_u32_e32 v120, 0x1000, v137
	v_pk_add_f32 v[142:143], v[142:143], v[14:15]
	ds_read2_b32 v[120:121], v120 offset0:64 offset1:132
	v_pk_add_f32 v[142:143], v[142:143], v[12:13]
	v_add_u32_e32 v126, 0x1200, v137
	v_pk_add_f32 v[142:143], v[142:143], v[10:11]
	ds_read2_b32 v[126:127], v126 offset0:72 offset1:140
	v_rcp_iflag_f32_e32 v184, v139
	v_add_u32_e32 v139, 0x1c00, v137
	v_add_u32_e32 v145, 21, v141
	v_pk_add_f32 v[142:143], v[142:143], v[8:9]
	ds_read2_b32 v[188:189], v139 offset0:112 offset1:180
	v_max_i32_e32 v139, 8, v187
	v_min_i32_e32 v145, s0, v145
	v_pk_add_f32 v[142:143], v[142:143], v[6:7]
	v_lshlrev_b32_e32 v168, 16, v159
	v_and_b32_e32 v169, 0xffff0000, v159
	v_add_u32_e32 v159, 0x1000, v194
	v_sub_u32_e32 v139, v145, v139
	v_pk_add_f32 v[142:143], v[142:143], v[4:5]
	v_lshlrev_b32_e32 v116, 16, v117
	v_and_b32_e32 v117, 0xffff0000, v117
	s_waitcnt lgkmcnt(2)
	v_lshlrev_b32_e32 v124, 16, v120
	v_and_b32_e32 v125, 0xffff0000, v120
	ds_read2_b32 v[182:183], v159 offset0:64 offset1:132
	v_add_u32_e32 v139, 8, v139
	v_pk_add_f32 v[142:143], v[142:143], v[2:3]
	v_lshlrev_b32_e32 v120, 16, v121
	v_and_b32_e32 v121, 0xffff0000, v121
	v_cvt_f32_i32_e32 v139, v139
	ds_read_b32 v137, v137 offset:8160
	v_pk_add_f32 v[116:117], v[142:143], v[116:117]
	v_pk_add_f32 v[28:29], v[124:125], v[28:29] neg_lo:[0,1] neg_hi:[0,1]
	v_rcp_iflag_f32_e32 v118, v118
	s_waitcnt lgkmcnt(3)
	v_lshlrev_b32_e32 v130, 16, v126
	v_and_b32_e32 v131, 0xffff0000, v126
	v_pk_add_f32 v[28:29], v[116:117], v[28:29]
	v_pk_add_f32 v[26:27], v[120:121], v[26:27] neg_lo:[0,1] neg_hi:[0,1]
	v_lshlrev_b32_e32 v126, 16, v127
	v_and_b32_e32 v127, 0xffff0000, v127
	v_pk_add_f32 v[26:27], v[28:29], v[26:27]
	v_pk_add_f32 v[24:25], v[130:131], v[24:25] neg_lo:[0,1] neg_hi:[0,1]
	v_add_u32_e32 v141, 22, v141
	v_pk_add_f32 v[24:25], v[26:27], v[24:25]
	v_pk_add_f32 v[22:23], v[126:127], v[22:23] neg_lo:[0,1] neg_hi:[0,1]
	v_add_u32_e32 v138, 8, v138
	s_waitcnt lgkmcnt(1)
	v_lshlrev_b32_e32 v186, 16, v182
	v_and_b32_e32 v187, 0xffff0000, v182
	v_rcp_iflag_f32_e32 v182, v139
	v_max_i32_e32 v139, 8, v195
	v_min_i32_e32 v141, s0, v141
	v_pk_add_f32 v[22:23], v[24:25], v[22:23]
	v_cvt_f32_i32_e32 v138, v138
	v_sub_u32_e32 v139, v141, v139
	v_pk_fma_f32 v[142:143], v[118:119], v[116:117], v[14:15] op_sel_hi:[0,1,1] neg_lo:[0,0,1] neg_hi:[0,0,1]
	v_pk_fma_f32 v[116:117], v[122:123], v[28:29], v[12:13] op_sel_hi:[0,1,1] neg_lo:[0,0,1] neg_hi:[0,0,1]
	s_waitcnt lgkmcnt(0)
	v_pk_fma_f32 v[28:29], v[136:137], v[26:27], v[10:11] op_sel_hi:[0,1,1] neg_lo:[0,0,1] neg_hi:[0,0,1]
	v_pk_fma_f32 v[26:27], v[128:129], v[24:25], v[8:9] op_sel_hi:[0,1,1] neg_lo:[0,0,1] neg_hi:[0,0,1]
	v_pk_fma_f32 v[24:25], v[140:141], v[22:23], v[6:7] op_sel_hi:[0,1,1] neg_lo:[0,0,1] neg_hi:[0,0,1]
	v_pk_add_f32 v[22:23], v[22:23], v[30:31]
	v_pk_add_f32 v[20:21], v[146:147], v[20:21] neg_lo:[0,1] neg_hi:[0,1]
	v_lshlrev_b32_e32 v152, 16, v153
	v_and_b32_e32 v153, 0xffff0000, v153
	v_add_u32_e32 v139, 8, v139
	v_pk_add_f32 v[20:21], v[22:23], v[20:21]
	v_pk_add_f32 v[18:19], v[154:155], v[18:19] neg_lo:[0,1] neg_hi:[0,1]
	v_lshlrev_b32_e32 v166, 16, v164
	v_and_b32_e32 v167, 0xffff0000, v164
	v_cvt_f32_i32_e32 v139, v139
	v_pk_add_f32 v[18:19], v[20:21], v[18:19]
	v_pk_add_f32 v[16:17], v[152:153], v[16:17] neg_lo:[0,1] neg_hi:[0,1]
	v_lshlrev_b32_e32 v164, 16, v165
	v_and_b32_e32 v165, 0xffff0000, v165
	ds_read_b32 v145, v194 offset:4896
	v_pk_add_f32 v[16:17], v[18:19], v[16:17]
	v_pk_add_f32 v[14:15], v[166:167], v[14:15] neg_lo:[0,1] neg_hi:[0,1]
	v_rcp_iflag_f32_e32 v138, v138
	v_rcp_iflag_f32_e32 v148, v148
	v_lshlrev_b32_e32 v178, 16, v176
	v_and_b32_e32 v179, 0xffff0000, v176
	v_pk_add_f32 v[14:15], v[16:17], v[14:15]
	v_pk_add_f32 v[12:13], v[164:165], v[12:13] neg_lo:[0,1] neg_hi:[0,1]
	v_lshlrev_b32_e32 v176, 16, v177
	v_and_b32_e32 v177, 0xffff0000, v177
	v_pk_add_f32 v[12:13], v[14:15], v[12:13]
	v_pk_add_f32 v[10:11], v[178:179], v[10:11] neg_lo:[0,1] neg_hi:[0,1]
	v_lshlrev_b32_e32 v190, 16, v188
	v_and_b32_e32 v191, 0xffff0000, v188
	v_rcp_iflag_f32_e32 v194, v139
	v_pk_add_f32 v[10:11], v[12:13], v[10:11]
	v_pk_add_f32 v[8:9], v[176:177], v[8:9] neg_lo:[0,1] neg_hi:[0,1]
	v_add_u32_e32 v149, v0, v133
	v_lshlrev_b32_e32 v188, 16, v189
	v_and_b32_e32 v189, 0xffff0000, v189
	v_cvt_pk_bf16_f32 v26, v26, v27
	v_pk_add_f32 v[8:9], v[10:11], v[8:9]
	v_pk_add_f32 v[6:7], v[190:191], v[6:7] neg_lo:[0,1] neg_hi:[0,1]
	ds_write_b32 v161, v26 offset:544
	v_cvt_pk_bf16_f32 v26, v24, v25
	v_pk_fma_f32 v[24:25], v[138:139], v[22:23], v[4:5] op_sel_hi:[0,1,1] neg_lo:[0,0,1] neg_hi:[0,0,1]
	v_pk_fma_f32 v[22:23], v[148:149], v[20:21], v[150:151] op_sel_hi:[0,1,1] neg_lo:[0,0,1] neg_hi:[0,0,1]
	s_waitcnt lgkmcnt(1)
	v_pk_fma_f32 v[20:21], v[144:145], v[18:19], v[156:157] op_sel_hi:[0,1,1] neg_lo:[0,0,1] neg_hi:[0,0,1]
	v_pk_add_f32 v[6:7], v[8:9], v[6:7]
	v_pk_add_f32 v[4:5], v[188:189], v[4:5] neg_lo:[0,1] neg_hi:[0,1]
	v_lshlrev_b32_e32 v180, 16, v171
	v_and_b32_e32 v181, 0xffff0000, v171
	v_lshlrev_b32_e32 v192, 16, v183
	v_and_b32_e32 v193, 0xffff0000, v183
	v_lshlrev_b32_e32 v200, 16, v145
	v_and_b32_e32 v201, 0xffff0000, v145
	v_and_b32_e32 v203, 0xffff0000, v137
	v_lshlrev_b32_e32 v202, 16, v137
	v_cvt_pk_bf16_f32 v118, v142, v143
	v_cvt_pk_bf16_f32 v116, v116, v117
	v_cvt_pk_bf16_f32 v28, v28, v29
	v_cvt_pk_bf16_f32 v24, v24, v25
	v_cvt_pk_bf16_f32 v22, v22, v23
	v_cvt_pk_bf16_f32 v20, v20, v21
	v_pk_add_f32 v[4:5], v[6:7], v[4:5]
	ds_write_b32 v149, v118
	ds_write2_b32 v161, v116, v28 offset1:68
	ds_write2_b32 v185, v26, v24 offset1:68
	ds_write2_b32 v185, v22, v20 offset0:136 offset1:204
	v_pk_fma_f32 v[18:19], v[160:161], v[16:17], v[162:163] op_sel_hi:[0,1,1] neg_lo:[0,0,1] neg_hi:[0,0,1]
	v_pk_fma_f32 v[16:17], v[158:159], v[14:15], v[168:169] op_sel_hi:[0,1,1] neg_lo:[0,0,1] neg_hi:[0,0,1]
	v_pk_fma_f32 v[14:15], v[172:173], v[12:13], v[174:175] op_sel_hi:[0,1,1] neg_lo:[0,0,1] neg_hi:[0,0,1]
	v_pk_fma_f32 v[12:13], v[170:171], v[10:11], v[180:181] op_sel_hi:[0,1,1] neg_lo:[0,0,1] neg_hi:[0,0,1]
	v_pk_fma_f32 v[10:11], v[184:185], v[8:9], v[186:187] op_sel_hi:[0,1,1] neg_lo:[0,0,1] neg_hi:[0,0,1]
	v_pk_fma_f32 v[8:9], v[182:183], v[6:7], v[192:193] op_sel_hi:[0,1,1] neg_lo:[0,0,1] neg_hi:[0,0,1]
	v_pk_fma_f32 v[6:7], v[194:195], v[4:5], v[200:201] op_sel_hi:[0,1,1] neg_lo:[0,0,1] neg_hi:[0,0,1]
	v_pk_add_f32 v[2:3], v[202:203], v[2:3] neg_lo:[0,1] neg_hi:[0,1]
	v_or_b32_e32 v22, 15, v135
	v_cvt_pk_bf16_f32 v18, v18, v19
	v_cvt_pk_bf16_f32 v16, v16, v17
	v_add_u32_e32 v17, 0x400, v185
	v_cvt_pk_bf16_f32 v14, v14, v15
	v_cvt_pk_bf16_f32 v12, v12, v13
	v_cvt_pk_bf16_f32 v10, v10, v11
	v_cvt_pk_bf16_f32 v8, v8, v9
	v_add_u32_e32 v9, 0x800, v185
	v_cvt_pk_bf16_f32 v6, v6, v7
	v_pk_add_f32 v[2:3], v[4:5], v[2:3]
	v_add_u32_e32 v4, s1, v22
	ds_write2_b32 v17, v18, v16 offset0:16 offset1:84
	ds_write2_b32 v17, v14, v12 offset0:152 offset1:220
	ds_write2_b32 v9, v10, v8 offset0:32 offset1:100
	ds_write_b32 v185, v6 offset:2720
	v_max_i32_e32 v21, 8, v4
	v_add_u32_e32 v23, 8, v4
	s_mov_b64 s[0:1], 0

.LBB0_418:
	v_mad_u64_u32 v[28:29], s[12:13], v22, s66, v[20:21]
	s_waitcnt vmcnt(4)
	ds_write_b128 v28, v[4:7]
	s_or_b64 exec, exec, s[10:11]
	s_and_saveexec_b64 s[10:11], s[0:1]
	s_cbranch_execz .LBB0_408
.LBB0_419:
	s_waitcnt vmcnt(4)
	v_mad_u64_u32 v[4:5], s[0:1], v23, s66, v[20:21]
	ds_write_b128 v4, v[0:3]
	s_or_b64 exec, exec, s[10:11]
	s_and_saveexec_b64 s[0:1], s[8:9]
	s_cbranch_execz .LBB0_409
.LBB0_420:
	s_waitcnt vmcnt(4)
	v_mad_u64_u32 v[0:1], s[8:9], v24, s66, v[20:21]
	ds_write_b128 v0, v[12:15]
	s_or_b64 exec, exec, s[0:1]
	s_and_saveexec_b64 s[0:1], s[4:5]
	s_cbranch_execz .LBB0_410
.LBB0_421:
	s_waitcnt vmcnt(4)
	v_mad_u64_u32 v[0:1], s[4:5], v25, s66, v[20:21]
	ds_write_b128 v0, v[8:11]
	s_or_b64 exec, exec, s[0:1]
	s_and_saveexec_b64 s[0:1], s[6:7]
	s_cbranch_execnz .LBB0_411
	s_branch .LBB0_412

.LBB0_460:
	s_or_b64 exec, exec, s[0:1]
	v_mad_u64_u32 v[14:15], s[0:1], v22, s66, v[20:21]
	v_mad_u64_u32 v[6:7], s[0:1], v23, s66, v[20:21]
	v_lshrrev_b32_e32 v0, 1, v21
	v_and_b32_e32 v1, 31, v132
	v_ashrrev_i32_e32 v96, 8, v21
	v_and_b32_e32 v119, 0x60, v0
	v_readlane_b32 s36, v254, 0
	v_lshlrev_b32_e32 v123, 6, v96
	v_readlane_b32 s48, v254, 12
	v_readlane_b32 s49, v254, 13
	v_bfe_u32 v97, v132, 5, 1
	v_readlane_b32 s40, v254, 4
	v_readlane_b32 s41, v254, 5
	s_mov_b64 s[12:13], s[48:49]
	v_readlane_b32 s42, v254, 6
	v_readlane_b32 s43, v254, 7
	v_readlane_b32 s44, v254, 8
	v_readlane_b32 s45, v254, 9
	s_mov_b64 s[4:5], s[40:41]
	s_mov_b64 s[8:9], s[44:45]
	v_ashrrev_i32_e32 v135, 2, v21
	v_and_b32_e32 v134, -16, v135
	v_mul_lo_u32 v133, v134, s66
	v_readlane_b32 s37, v254, 1
	v_readlane_b32 s38, v254, 2
	v_readlane_b32 s39, v254, 3
	v_readlane_b32 s46, v254, 10
	v_readlane_b32 s47, v254, 11
	v_readlane_b32 s50, v254, 14
	v_readlane_b32 s51, v254, 15
	s_mov_b64 s[6:7], s[42:43]
	s_waitcnt vmcnt(3)
	ds_write_b128 v14, v[128:131] offset:39168
	s_waitcnt vmcnt(2)
	ds_write_b128 v6, v[32:35] offset:39168
	v_mad_u64_u32 v[6:7], s[0:1], v24, s66, v[20:21]
	s_waitcnt vmcnt(1)
	ds_write_b128 v6, v[36:39] offset:39168
	v_mad_u64_u32 v[6:7], s[0:1], v25, s66, v[20:21]
	v_readlane_b32 s0, v255, 1
	s_waitcnt vmcnt(0)
	ds_write_b128 v6, v[40:43] offset:39168
	v_or3_b32 v198, v1, s0, v119
	v_readlane_b32 s0, v254, 57
	v_mov_b64_e32 v[2:3], s[52:53]
	s_nop 0
	v_add_u32_e32 v0, s0, v123
	v_mad_u64_u32 v[2:3], s[0:1], v198, s62, v[2:3]
	v_lshl_or_b32 v112, v97, 2, v0
	s_add_u32 s0, s12, s88
	s_addc_u32 s1, s13, s89
	v_ashrrev_i32_e32 v113, 31, v112
	s_add_u32 s4, s8, s88
	v_lshlrev_b64 v[4:5], 2, v[112:113]
	s_addc_u32 s5, s9, s89
	v_lshl_add_u64 v[2:3], v[112:113], 1, v[2:3]
	v_lshl_add_u64 v[6:7], s[0:1], 0, v[4:5]
	global_load_dwordx2 v[114:115], v[2:3], off offset:3584
	v_lshl_add_u64 v[4:5], s[4:5], 0, v[4:5]
	global_load_dwordx4 v[92:95], v[6:7], off
	global_load_dwordx4 v[88:91], v[4:5], off
	global_load_dwordx2 v[110:111], v[2:3], off offset:3600
	global_load_dwordx4 v[84:87], v[6:7], off offset:32
	global_load_dwordx4 v[80:83], v[4:5], off offset:32
	global_load_dwordx2 v[108:109], v[2:3], off offset:3616
	global_load_dwordx4 v[76:79], v[6:7], off offset:64
	global_load_dwordx4 v[72:75], v[4:5], off offset:64
	global_load_dwordx2 v[106:107], v[2:3], off offset:3632
	global_load_dwordx4 v[68:71], v[6:7], off offset:96
	global_load_dwordx4 v[64:67], v[4:5], off offset:96
	global_load_dwordx2 v[104:105], v[2:3], off offset:3648
	global_load_dwordx4 v[60:63], v[6:7], off offset:128
	global_load_dwordx4 v[56:59], v[4:5], off offset:128
	global_load_dwordx2 v[102:103], v[2:3], off offset:3664
	global_load_dwordx4 v[52:55], v[6:7], off offset:160
	global_load_dwordx4 v[48:51], v[4:5], off offset:160
	global_load_dwordx2 v[100:101], v[2:3], off offset:3680
	global_load_dwordx4 v[44:47], v[6:7], off offset:192
	global_load_dwordx4 v[40:43], v[4:5], off offset:192
	global_load_dwordx2 v[98:99], v[2:3], off offset:3696
	global_load_dwordx4 v[36:39], v[6:7], off offset:224
	global_load_dwordx4 v[32:35], v[4:5], off offset:224
	s_cmp_lt_i32 s96, 2
	s_waitcnt lgkmcnt(0)
	s_barrier
	s_cbranch_scc1 .LBB0_470
	s_cmp_gt_i32 s96, 2
	s_mov_b64 s[0:1], -1
	s_cbranch_scc0 .LBB0_463
	v_lshlrev_b32_e32 v0, 2, v132
	v_and_b32_e32 v129, 0xfc, v0
	v_add_u32_e32 v137, v133, v129
	ds_read2_b32 v[2:3], v137 offset1:68
	ds_read2_b32 v[4:5], v137 offset0:136 offset1:204
	v_readlane_b32 s1, v255, 3
	v_or_b32_e32 v122, 1, v134
	v_readlane_b32 s0, v255, 0
	v_add_u32_e32 v124, s1, v122
	v_max_i32_e32 v125, 8, v124
	v_or_b32_e32 v124, 8, v124
	v_add_u32_e32 v0, 0x400, v137
	v_min_i32_e32 v124, s0, v124
	s_waitcnt lgkmcnt(1)
	v_lshlrev_b32_e32 v28, 16, v2
	v_and_b32_e32 v29, 0xffff0000, v2
	v_lshlrev_b32_e32 v26, 16, v3
	v_and_b32_e32 v27, 0xffff0000, v3
	ds_read2_b32 v[2:3], v0 offset0:16 offset1:84
	v_sub_u32_e32 v124, v124, v125
	v_add_u32_e32 v124, 8, v124
	v_cvt_f32_i32_e32 v126, v124
	s_waitcnt lgkmcnt(1)
	v_lshlrev_b32_e32 v24, 16, v4
	v_and_b32_e32 v25, 0xffff0000, v4
	v_lshlrev_b32_e32 v22, 16, v5
	v_and_b32_e32 v23, 0xffff0000, v5
	ds_read2_b32 v[4:5], v0 offset0:152 offset1:220
	v_add_u32_e32 v0, 0x800, v137
	s_waitcnt lgkmcnt(1)
	v_lshlrev_b32_e32 v30, 16, v2
	v_and_b32_e32 v31, 0xffff0000, v2
	v_lshlrev_b32_e32 v20, 16, v3
	v_and_b32_e32 v21, 0xffff0000, v3
	ds_read2_b32 v[2:3], v0 offset0:32 offset1:100
	v_add_u32_e32 v141, s1, v134
	v_mul_lo_u32 v140, v122, s66
	v_rcp_iflag_f32_e32 v122, v126
	v_add_u32_e32 v126, 2, v141
	v_add_u32_e32 v169, 10, v141
	v_add_u32_e32 v130, 3, v141
	v_add_u32_e32 v173, 11, v141
	v_max_i32_e32 v126, 8, v126
	v_min_i32_e32 v127, s0, v169
	v_max_i32_e32 v130, 8, v130
	v_min_i32_e32 v131, s0, v173
	v_sub_u32_e32 v126, v127, v126
	v_sub_u32_e32 v130, v131, v130
	s_waitcnt lgkmcnt(1)
	v_lshlrev_b32_e32 v18, 16, v4
	v_and_b32_e32 v19, 0xffff0000, v4
	v_lshlrev_b32_e32 v16, 16, v5
	v_and_b32_e32 v17, 0xffff0000, v5
	ds_read2_b32 v[4:5], v0 offset0:168 offset1:236
	v_add_u32_e32 v0, 0xc00, v137
	v_add_u32_e32 v126, 8, v126
	v_add_u32_e32 v130, 8, v130
	s_waitcnt lgkmcnt(1)
	v_lshlrev_b32_e32 v14, 16, v2
	v_and_b32_e32 v15, 0xffff0000, v2
	v_lshlrev_b32_e32 v12, 16, v3
	v_and_b32_e32 v13, 0xffff0000, v3
	ds_read2_b32 v[2:3], v0 offset0:48 offset1:116
	ds_read2_b32 v[116:117], v0 offset0:184 offset1:252
	v_cvt_f32_i32_e32 v128, v126
	v_cvt_f32_i32_e32 v138, v130
	v_add_u32_e32 v181, 12, v141
	s_waitcnt lgkmcnt(2)
	v_lshlrev_b32_e32 v10, 16, v4
	v_rcp_iflag_f32_e32 v136, v128
	v_rcp_iflag_f32_e32 v128, v138
	v_add_u32_e32 v138, 4, v141
	v_and_b32_e32 v11, 0xffff0000, v4
	v_lshlrev_b32_e32 v8, 16, v5
	v_and_b32_e32 v9, 0xffff0000, v5
	s_waitcnt lgkmcnt(1)
	v_lshlrev_b32_e32 v6, 16, v2
	v_and_b32_e32 v7, 0xffff0000, v2
	v_lshlrev_b32_e32 v4, 16, v3
	v_and_b32_e32 v5, 0xffff0000, v3
	s_waitcnt lgkmcnt(0)
	v_lshlrev_b32_e32 v2, 16, v116
	v_and_b32_e32 v3, 0xffff0000, v116
	v_or_b32_e32 v116, 8, v141
	v_max_i32_e32 v138, 8, v138
	v_min_i32_e32 v139, s0, v181
	v_max_i32_e32 v0, 8, v141
	v_min_i32_e32 v116, s0, v116
	v_sub_u32_e32 v138, v139, v138
	v_sub_u32_e32 v0, v116, v0
	v_add_u32_e32 v138, 8, v138
	v_add_u32_e32 v0, 8, v0
	v_cvt_f32_i32_e32 v142, v138
	v_add_u32_e32 v138, 0x1400, v137
	v_cvt_f32_i32_e32 v118, v0
	v_or_b32_e32 v0, 0x12100, v129
	ds_read2_b32 v[138:139], v138 offset0:80 offset1:148
	v_add_u32_e32 v144, 0x330, v140
	v_add_u32_e32 v185, v0, v144
	v_add_u32_e32 v194, v144, v129
	v_add_u32_e32 v144, 6, v141
	v_add_u32_e32 v195, 14, v141
	v_max_i32_e32 v146, 8, v144
	v_min_i32_e32 v147, s0, v195
	v_sub_u32_e32 v146, v147, v146
	v_add_u32_e32 v146, 8, v146
	v_cvt_f32_i32_e32 v148, v146
	s_waitcnt lgkmcnt(0)
	v_lshlrev_b32_e32 v146, 16, v139
	v_and_b32_e32 v147, 0xffff0000, v139
	v_add_u32_e32 v139, 0x1600, v137
	ds_read2_b32 v[152:153], v139 offset0:88 offset1:156
	v_add_u32_e32 v139, 7, v141
	v_add_u32_e32 v151, 15, v141
	v_add_u32_e32 v161, v0, v140
	v_rcp_iflag_f32_e32 v140, v142
	v_lshlrev_b32_e32 v142, 16, v138
	v_and_b32_e32 v143, 0xffff0000, v138
	v_add_u32_e32 v138, 5, v141
	v_add_u32_e32 v187, 13, v141
	v_max_i32_e32 v139, 8, v139
	v_min_i32_e32 v151, s0, v151
	v_max_i32_e32 v138, 8, v138
	v_min_i32_e32 v145, s0, v187
	v_add_u32_e32 v144, 0x800, v194
	v_sub_u32_e32 v139, v151, v139
	v_sub_u32_e32 v138, v145, v138
	ds_read2_b32 v[144:145], v144 offset0:168 offset1:236
	v_add_u32_e32 v139, 8, v139
	v_cvt_f32_i32_e32 v139, v139
	s_waitcnt lgkmcnt(1)
	v_lshlrev_b32_e32 v154, 16, v152
	v_and_b32_e32 v155, 0xffff0000, v152
	s_waitcnt lgkmcnt(0)
	v_lshlrev_b32_e32 v150, 16, v144
	v_and_b32_e32 v151, 0xffff0000, v144
	v_rcp_iflag_f32_e32 v144, v139
	v_add_u32_e32 v139, 8, v141
	v_add_u32_e32 v152, 16, v141
	v_max_i32_e32 v139, 8, v139
	v_min_i32_e32 v152, s0, v152
	v_sub_u32_e32 v139, v152, v139
	v_add_u32_e32 v139, 8, v139
	v_cvt_f32_i32_e32 v139, v139
	v_lshlrev_b32_e32 v156, 16, v145
	v_and_b32_e32 v157, 0xffff0000, v145
	v_add_u32_e32 v145, 17, v141
	v_rcp_iflag_f32_e32 v160, v139
	v_add_u32_e32 v139, 0x1800, v137
	ds_read2_b32 v[164:165], v139 offset0:96 offset1:164
	v_add_u32_e32 v139, 9, v141
	v_max_i32_e32 v139, 8, v139
	v_min_i32_e32 v145, s0, v145
	v_add_u32_e32 v170, 0xc00, v194
	v_sub_u32_e32 v139, v145, v139
	ds_read2_b32 v[158:159], v170 offset0:48 offset1:116
	v_add_u32_e32 v139, 8, v139
	v_cvt_f32_i32_e32 v139, v139
	v_add_u32_e32 v145, 18, v141
	v_min_i32_e32 v145, s0, v145
	s_waitcnt lgkmcnt(0)
	v_lshlrev_b32_e32 v162, 16, v158
	v_and_b32_e32 v163, 0xffff0000, v158
	v_rcp_iflag_f32_e32 v158, v139
	v_max_i32_e32 v139, 8, v169
	v_sub_u32_e32 v139, v145, v139
	v_add_u32_e32 v139, 8, v139
	v_cvt_f32_i32_e32 v139, v139
	v_add_u32_e32 v145, 19, v141
	v_min_i32_e32 v145, s0, v145
	ds_read2_b32 v[170:171], v170 offset0:184 offset1:252
	v_rcp_iflag_f32_e32 v172, v139
	v_add_u32_e32 v139, 0x1a00, v137
	ds_read2_b32 v[176:177], v139 offset0:104 offset1:172
	v_max_i32_e32 v139, 8, v173
	v_sub_u32_e32 v139, v145, v139
	v_add_u32_e32 v139, 8, v139
	v_cvt_f32_i32_e32 v139, v139
	v_pk_add_f32 v[204:205], v[28:29], 0 op_sel_hi:[1,0]
	v_add_u32_e32 v145, 20, v141
	v_pk_add_f32 v[204:205], v[204:205], v[26:27]
	s_waitcnt lgkmcnt(1)
	v_lshlrev_b32_e32 v174, 16, v170
	v_pk_add_f32 v[204:205], v[204:205], v[24:25]
	v_and_b32_e32 v175, 0xffff0000, v170
	v_pk_add_f32 v[204:205], v[204:205], v[22:23]
	v_rcp_iflag_f32_e32 v170, v139
	v_max_i32_e32 v139, 8, v181
	v_min_i32_e32 v145, s0, v145
	v_pk_add_f32 v[204:205], v[204:205], v[30:31]
	v_sub_u32_e32 v139, v145, v139
	v_pk_add_f32 v[204:205], v[204:205], v[20:21]
	v_add_u32_e32 v139, 8, v139
	v_pk_add_f32 v[30:31], v[142:143], v[30:31] neg_lo:[0,1] neg_hi:[0,1]
	v_pk_add_f32 v[142:143], v[204:205], v[18:19]
	v_cvt_f32_i32_e32 v139, v139
	v_pk_add_f32 v[142:143], v[142:143], v[16:17]
	v_add_u32_e32 v120, 0x1000, v137
	v_pk_add_f32 v[142:143], v[142:143], v[14:15]
	ds_read2_b32 v[120:121], v120 offset0:64 offset1:132
	v_pk_add_f32 v[142:143], v[142:143], v[12:13]
	v_add_u32_e32 v126, 0x1200, v137
	v_pk_add_f32 v[142:143], v[142:143], v[10:11]
	ds_read2_b32 v[126:127], v126 offset0:72 offset1:140
	v_rcp_iflag_f32_e32 v184, v139
	v_add_u32_e32 v139, 0x1c00, v137
	v_add_u32_e32 v145, 21, v141
	v_pk_add_f32 v[142:143], v[142:143], v[8:9]
	ds_read2_b32 v[188:189], v139 offset0:112 offset1:180
	v_max_i32_e32 v139, 8, v187
	v_min_i32_e32 v145, s0, v145
	v_pk_add_f32 v[142:143], v[142:143], v[6:7]
	v_lshlrev_b32_e32 v168, 16, v159
	v_and_b32_e32 v169, 0xffff0000, v159
	v_add_u32_e32 v159, 0x1000, v194
	v_sub_u32_e32 v139, v145, v139
	v_pk_add_f32 v[142:143], v[142:143], v[4:5]
	v_lshlrev_b32_e32 v116, 16, v117
	v_and_b32_e32 v117, 0xffff0000, v117
	s_waitcnt lgkmcnt(2)
	v_lshlrev_b32_e32 v124, 16, v120
	v_and_b32_e32 v125, 0xffff0000, v120
	ds_read2_b32 v[182:183], v159 offset0:64 offset1:132
	v_add_u32_e32 v139, 8, v139
	v_pk_add_f32 v[142:143], v[142:143], v[2:3]
	v_lshlrev_b32_e32 v120, 16, v121
	v_and_b32_e32 v121, 0xffff0000, v121
	v_cvt_f32_i32_e32 v139, v139
	ds_read_b32 v137, v137 offset:8160
	v_pk_add_f32 v[116:117], v[142:143], v[116:117]
	v_pk_add_f32 v[28:29], v[124:125], v[28:29] neg_lo:[0,1] neg_hi:[0,1]
	v_rcp_iflag_f32_e32 v118, v118
	s_waitcnt lgkmcnt(3)
	v_lshlrev_b32_e32 v130, 16, v126
	v_and_b32_e32 v131, 0xffff0000, v126
	v_pk_add_f32 v[28:29], v[116:117], v[28:29]
	v_pk_add_f32 v[26:27], v[120:121], v[26:27] neg_lo:[0,1] neg_hi:[0,1]
	v_lshlrev_b32_e32 v126, 16, v127
	v_and_b32_e32 v127, 0xffff0000, v127
	v_pk_add_f32 v[26:27], v[28:29], v[26:27]
	v_pk_add_f32 v[24:25], v[130:131], v[24:25] neg_lo:[0,1] neg_hi:[0,1]
	v_add_u32_e32 v141, 22, v141
	v_pk_add_f32 v[24:25], v[26:27], v[24:25]
	v_pk_add_f32 v[22:23], v[126:127], v[22:23] neg_lo:[0,1] neg_hi:[0,1]
	v_add_u32_e32 v138, 8, v138
	s_waitcnt lgkmcnt(1)
	v_lshlrev_b32_e32 v186, 16, v182
	v_and_b32_e32 v187, 0xffff0000, v182
	v_rcp_iflag_f32_e32 v182, v139
	v_max_i32_e32 v139, 8, v195
	v_min_i32_e32 v141, s0, v141
	v_pk_add_f32 v[22:23], v[24:25], v[22:23]
	v_cvt_f32_i32_e32 v138, v138
	v_sub_u32_e32 v139, v141, v139
	v_pk_fma_f32 v[142:143], v[118:119], v[116:117], v[14:15] op_sel_hi:[0,1,1] neg_lo:[0,0,1] neg_hi:[0,0,1]
	v_pk_fma_f32 v[116:117], v[122:123], v[28:29], v[12:13] op_sel_hi:[0,1,1] neg_lo:[0,0,1] neg_hi:[0,0,1]
	s_waitcnt lgkmcnt(0)
	v_pk_fma_f32 v[28:29], v[136:137], v[26:27], v[10:11] op_sel_hi:[0,1,1] neg_lo:[0,0,1] neg_hi:[0,0,1]
	v_pk_fma_f32 v[26:27], v[128:129], v[24:25], v[8:9] op_sel_hi:[0,1,1] neg_lo:[0,0,1] neg_hi:[0,0,1]
	v_pk_fma_f32 v[24:25], v[140:141], v[22:23], v[6:7] op_sel_hi:[0,1,1] neg_lo:[0,0,1] neg_hi:[0,0,1]
	v_pk_add_f32 v[22:23], v[22:23], v[30:31]
	v_pk_add_f32 v[20:21], v[146:147], v[20:21] neg_lo:[0,1] neg_hi:[0,1]
	v_lshlrev_b32_e32 v152, 16, v153
	v_and_b32_e32 v153, 0xffff0000, v153
	v_add_u32_e32 v139, 8, v139
	v_pk_add_f32 v[20:21], v[22:23], v[20:21]
	v_pk_add_f32 v[18:19], v[154:155], v[18:19] neg_lo:[0,1] neg_hi:[0,1]
	v_lshlrev_b32_e32 v166, 16, v164
	v_and_b32_e32 v167, 0xffff0000, v164
	v_cvt_f32_i32_e32 v139, v139
	v_pk_add_f32 v[18:19], v[20:21], v[18:19]
	v_pk_add_f32 v[16:17], v[152:153], v[16:17] neg_lo:[0,1] neg_hi:[0,1]
	v_lshlrev_b32_e32 v164, 16, v165
	v_and_b32_e32 v165, 0xffff0000, v165
	ds_read_b32 v145, v194 offset:4896
	v_pk_add_f32 v[16:17], v[18:19], v[16:17]
	v_pk_add_f32 v[14:15], v[166:167], v[14:15] neg_lo:[0,1] neg_hi:[0,1]
	v_rcp_iflag_f32_e32 v138, v138
	v_rcp_iflag_f32_e32 v148, v148
	v_lshlrev_b32_e32 v178, 16, v176
	v_and_b32_e32 v179, 0xffff0000, v176
	v_pk_add_f32 v[14:15], v[16:17], v[14:15]
	v_pk_add_f32 v[12:13], v[164:165], v[12:13] neg_lo:[0,1] neg_hi:[0,1]
	v_lshlrev_b32_e32 v176, 16, v177
	v_and_b32_e32 v177, 0xffff0000, v177
	v_pk_add_f32 v[12:13], v[14:15], v[12:13]
	v_pk_add_f32 v[10:11], v[178:179], v[10:11] neg_lo:[0,1] neg_hi:[0,1]
	v_lshlrev_b32_e32 v190, 16, v188
	v_and_b32_e32 v191, 0xffff0000, v188
	v_rcp_iflag_f32_e32 v194, v139
	v_pk_add_f32 v[10:11], v[12:13], v[10:11]
	v_pk_add_f32 v[8:9], v[176:177], v[8:9] neg_lo:[0,1] neg_hi:[0,1]
	v_add_u32_e32 v149, v0, v133
	v_lshlrev_b32_e32 v188, 16, v189
	v_and_b32_e32 v189, 0xffff0000, v189
	v_cvt_pk_bf16_f32 v26, v26, v27
	v_pk_add_f32 v[8:9], v[10:11], v[8:9]
	v_pk_add_f32 v[6:7], v[190:191], v[6:7] neg_lo:[0,1] neg_hi:[0,1]
	ds_write_b32 v161, v26 offset:544
	v_cvt_pk_bf16_f32 v26, v24, v25
	v_pk_fma_f32 v[24:25], v[138:139], v[22:23], v[4:5] op_sel_hi:[0,1,1] neg_lo:[0,0,1] neg_hi:[0,0,1]
	v_pk_fma_f32 v[22:23], v[148:149], v[20:21], v[150:151] op_sel_hi:[0,1,1] neg_lo:[0,0,1] neg_hi:[0,0,1]
	s_waitcnt lgkmcnt(1)
	v_pk_fma_f32 v[20:21], v[144:145], v[18:19], v[156:157] op_sel_hi:[0,1,1] neg_lo:[0,0,1] neg_hi:[0,0,1]
	v_pk_add_f32 v[6:7], v[8:9], v[6:7]
	v_pk_add_f32 v[4:5], v[188:189], v[4:5] neg_lo:[0,1] neg_hi:[0,1]
	v_lshlrev_b32_e32 v180, 16, v171
	v_and_b32_e32 v181, 0xffff0000, v171
	v_lshlrev_b32_e32 v192, 16, v183
	v_and_b32_e32 v193, 0xffff0000, v183
	v_lshlrev_b32_e32 v200, 16, v145
	v_and_b32_e32 v201, 0xffff0000, v145
	v_and_b32_e32 v203, 0xffff0000, v137
	v_lshlrev_b32_e32 v202, 16, v137
	v_cvt_pk_bf16_f32 v118, v142, v143
	v_cvt_pk_bf16_f32 v116, v116, v117
	v_cvt_pk_bf16_f32 v28, v28, v29
	v_cvt_pk_bf16_f32 v24, v24, v25
	v_cvt_pk_bf16_f32 v22, v22, v23
	v_cvt_pk_bf16_f32 v20, v20, v21
	v_pk_add_f32 v[4:5], v[6:7], v[4:5]
	ds_write_b32 v149, v118
	ds_write2_b32 v161, v116, v28 offset1:68
	ds_write2_b32 v185, v26, v24 offset1:68
	ds_write2_b32 v185, v22, v20 offset0:136 offset1:204
	v_pk_fma_f32 v[18:19], v[160:161], v[16:17], v[162:163] op_sel_hi:[0,1,1] neg_lo:[0,0,1] neg_hi:[0,0,1]
	v_pk_fma_f32 v[16:17], v[158:159], v[14:15], v[168:169] op_sel_hi:[0,1,1] neg_lo:[0,0,1] neg_hi:[0,0,1]
	v_pk_fma_f32 v[14:15], v[172:173], v[12:13], v[174:175] op_sel_hi:[0,1,1] neg_lo:[0,0,1] neg_hi:[0,0,1]
	v_pk_fma_f32 v[12:13], v[170:171], v[10:11], v[180:181] op_sel_hi:[0,1,1] neg_lo:[0,0,1] neg_hi:[0,0,1]
	v_pk_fma_f32 v[10:11], v[184:185], v[8:9], v[186:187] op_sel_hi:[0,1,1] neg_lo:[0,0,1] neg_hi:[0,0,1]
	v_pk_fma_f32 v[8:9], v[182:183], v[6:7], v[192:193] op_sel_hi:[0,1,1] neg_lo:[0,0,1] neg_hi:[0,0,1]
	v_pk_fma_f32 v[6:7], v[194:195], v[4:5], v[200:201] op_sel_hi:[0,1,1] neg_lo:[0,0,1] neg_hi:[0,0,1]
	v_pk_add_f32 v[2:3], v[202:203], v[2:3] neg_lo:[0,1] neg_hi:[0,1]
	v_or_b32_e32 v22, 15, v135
	v_cvt_pk_bf16_f32 v18, v18, v19
	v_cvt_pk_bf16_f32 v16, v16, v17
	v_add_u32_e32 v17, 0x400, v185
	v_cvt_pk_bf16_f32 v14, v14, v15
	v_cvt_pk_bf16_f32 v12, v12, v13
	v_cvt_pk_bf16_f32 v10, v10, v11
	v_cvt_pk_bf16_f32 v8, v8, v9
	v_add_u32_e32 v9, 0x800, v185
	v_cvt_pk_bf16_f32 v6, v6, v7
	v_pk_add_f32 v[2:3], v[4:5], v[2:3]
	v_add_u32_e32 v4, s1, v22
	ds_write2_b32 v17, v18, v16 offset0:16 offset1:84
	ds_write2_b32 v17, v14, v12 offset0:152 offset1:220
	ds_write2_b32 v9, v10, v8 offset0:32 offset1:100
	ds_write_b32 v185, v6 offset:2720
	v_max_i32_e32 v21, 8, v4
	v_add_u32_e32 v23, 8, v4
	s_mov_b64 s[0:1], 0

.LBB0_478:
	s_mov_b64 s[4:5], 0xb8fb000
	s_getreg_b32 s6, hwreg(HW_REG_XCC_ID, 0, 4)
	v_mbcnt_lo_u32_b32 v0, -1, 0
	v_mbcnt_hi_u32_b32 v0, -1, v0
	s_waitcnt vmcnt(0)
	s_waitcnt lgkmcnt(0)
	v_sub_u32_e32 v0, 0, v0
	v_cmp_eq_u32_e32 vcc, s3, v0
	s_barrier
	s_and_saveexec_b64 s[0:1], vcc
	s_cbranch_execz .LBB0_532
	v_mov_b32_e32 v2, 0x23808
	s_waitcnt vmcnt(0) lgkmcnt(0)
	ds_read_b32 v2, v2
	s_add_u32 s8, s28, s4
	s_addc_u32 s9, s29, s5
	s_waitcnt lgkmcnt(0)
	v_readfirstlane_b32 s10, v2
	s_cmp_eq_u32 s10, 0
	s_cbranch_scc1 .Lgs1_global
	s_and_b32 s10, s85, 7
	s_lshl_b32 s10, s10, 8
	s_add_i32 s10, s10, 0x480
	v_mov_b32_e32 v3, s10
	v_mov_b32_e32 v4, 1
	v_mov_b32_e32 v5, 0x100
	global_atomic_add v5, v4, s[8:9]
	global_atomic_add v6, v3, v4, s[8:9] sc0
	s_waitcnt vmcnt(0)
	v_and_b32_e32 v6, 0xffffffe0, v6
	v_add_u32_e32 v6, 32, v6
	s_mov_b32 s11, 0
	buffer_inv sc1

.LBB0_630:
	s_mov_b64 s[4:5], 0xb8fb000
	s_getreg_b32 s6, hwreg(HW_REG_XCC_ID, 0, 4)
	v_mbcnt_lo_u32_b32 v0, -1, 0
	v_mbcnt_hi_u32_b32 v0, -1, v0
	s_waitcnt vmcnt(0)
	s_waitcnt lgkmcnt(0)
	v_sub_u32_e32 v0, 0, v0
	v_cmp_eq_u32_e32 vcc, s3, v0
	s_barrier
	s_and_saveexec_b64 s[0:1], vcc
	s_cbranch_execz .LBB0_186
	v_mov_b32_e32 v2, 0x23808
	s_waitcnt vmcnt(0) lgkmcnt(0)
	ds_read_b32 v2, v2
	s_add_u32 s8, s28, s4
	s_addc_u32 s9, s29, s5
	s_waitcnt lgkmcnt(0)
	v_readfirstlane_b32 s10, v2
	s_cmp_eq_u32 s10, 0
	s_cbranch_scc1 .Lgs2_global
	s_and_b32 s10, s85, 7
	s_lshl_b32 s10, s10, 8
	s_add_i32 s10, s10, 0x480
	v_mov_b32_e32 v3, s10
	v_mov_b32_e32 v4, 1
	v_mov_b32_e32 v5, 0x100
	global_atomic_add v6, v3, v4, s[8:9] sc0
	s_waitcnt vmcnt(0)
	v_and_b32_e32 v6, 0xffffffe0, v6
	v_add_u32_e32 v6, 32, v6
	s_mov_b32 s11, 0
	buffer_inv sc1
